# as previous; the 65 s_nop after M0 writes replaced by scheduling the address add between the M0 write and its LDS-DMA (hipcc's own pattern)
# baseline (speedup 1.0000x reference)
; #define PG8_STAGE(bufoff, gbase, voff) do { _Pragma("unroll") for (int _i = 0; _i < 2; ++_i) \
;         __builtin_amdgcn_global_load_lds((const unsigned*)((const char*)(gbase) + (voff)[_i]), (LAS unsigned*)(lds + (bufoff) + ldsw + _i * 8192), 16, 0, 0); } while (0)
; #define PG8_LDA(dst, b, h) do { _Pragma("unroll") for (int m = 0; m < 4; ++m) _Pragma("unroll") for (int k = 0; k < 2; ++k) dst[m][k] = *(const LAS bf16x8*)(lds + PG8_SA(b, h) + aoff + m * 2048 + k * 1024); } while (0)
; #define PG8_LDB(dst, b, h) do { _Pragma("unroll") for (int n = 0; n < 2; ++n) _Pragma("unroll") for (int k = 0; k < 2; ++k) dst[n][k] = *(const LAS bf16x8*)(lds + PG8_SB(b, h) + boff + n * 2048 + k * 1024); } while (0)
; #define PG8_WAIT_V(n) asm volatile("s_waitcnt vmcnt(" #n ")" ::: "memory")
; #define PG8_WAIT_L(n) asm volatile("s_waitcnt lgkmcnt(" #n ")" ::: "memory")
; #define PG8_BAR __builtin_amdgcn_s_barrier()
; #define PG8_SCHED __builtin_amdgcn_sched_barrier(0)
; template <class Epi>
; __device__ __forceinline__ void gemm_phase(LAS unsigned char* lds, const Gemm g, const StaticOrder& S, const Epi& E) {
;     ...
;         const bool has_next = S.next(ui + 1, nxt);
;         const char* nA = has_next ? (const char*)g.A + (size_t)nxt.pm * tstepA + (size_t)nxt.kt0 * kstep : cA; const char* nB = has_next ? (const char*)g.Bt + (size_t)nxt.pn * tstepB + (size_t)nxt.kt0 * kstep : cB;
;         const int nt = cur.nkt;
;         for (int t = 0; t < nt; t += 2) {
;             const bool last = (t == nt - 2);
;             const char* a1 = cA + (size_t)(t + 1) * kstep;
;             const char* a2 = last ? nA : cA + (size_t)(t + 2) * kstep; const char* b2 = last ? nB : cB + (size_t)(t + 2) * kstep;
;             const char* a3 = a2 + kstep; const char* b3 = b2 + kstep;
;             PG8_LDB(B0, 0, 0); PG8_SCHED; PG8_LDA(At, 0, 0); PG8_STAGE(PG8_SA(1, 1), a1 + hstepA, voffA);
;             PG8_WAIT_L(8); PG8_BAR; PG8_WAIT_L(0); PG8_MMA(0, 0, At, B0); PG8_BAR; PG8_SCHED;
;             PG8_LDB(B1, 0, 1); PG8_STAGE(PG8_SB(0, 0), b2, voffB);
;             PG8_BAR; PG8_WAIT_L(0); PG8_MMA(0, 1, At, B1); PG8_BAR;
;             PG8_LDA(At, 0, 1); PG8_STAGE(PG8_SA(0, 0), a2, voffA);
;             PG8_BAR; PG8_WAIT_L(0); PG8_MMA(1, 0, At, B0); PG8_BAR; PG8_SCHED;
;             PG8_STAGE(PG8_SB(0, 1), b2 + hstepB, voffB);
;             PG8_WAIT_V(6); PG8_BAR; PG8_MMA(1, 1, At, B1); PG8_BAR;
.LBB0_119:
	s_add_u32 s55, s62, 0xfffc0080
	s_addc_u32 s61, s63, -1
	s_cmp_eq_u32 s33, 12
	s_cselect_b32 s67, s57, s61
	s_cselect_b32 s66, s56, s55
	s_cselect_b32 s65, s59, s31
	s_cselect_b32 s64, s58, s9
	ds_read_b128 v[146:149], v154
	ds_read_b128 v[158:161], v154 offset:1024
	ds_read_b128 v[162:165], v154 offset:2048
	ds_read_b128 v[166:169], v154 offset:3072
	ds_read_b128 v[170:173], v155
	ds_read_b128 v[174:177], v155 offset:1024
	ds_read_b128 v[178:181], v155 offset:2048
	ds_read_b128 v[182:185], v155 offset:3072
	ds_read_b128 v[186:189], v155 offset:4096
	ds_read_b128 v[190:193], v155 offset:5120
	ds_read_b128 v[194:197], v155 offset:6144
	ds_read_b128 v[198:201], v155 offset:7168
	ds_read_b128 v[202:205], v156
	ds_read_b128 v[206:209], v156 offset:1024
	ds_read_b128 v[210:213], v156 offset:2048
	ds_read_b128 v[214:217], v156 offset:3072
	s_add_i32 m0, s68, 0xc000
	v_lshl_add_u64 v[242:243], s[62:63], 0, v[138:139]
	global_load_lds_dwordx4 v[242:243], off
	s_add_i32 m0, s68, 0xe000
	v_lshl_add_u64 v[242:243], s[62:63], 0, v[140:141]
	global_load_lds_dwordx4 v[242:243], off
	s_waitcnt vmcnt(8) lgkmcnt(0)
	s_barrier
	v_mfma_f32_16x16x32_bf16 v[124:127], v[146:149], v[170:173], v[124:127]
	v_mfma_f32_16x16x32_bf16 v[120:123], v[162:165], v[170:173], v[120:123]
	v_mfma_f32_16x16x32_bf16 v[108:111], v[146:149], v[178:181], v[108:111]
	v_mfma_f32_16x16x32_bf16 v[104:107], v[162:165], v[178:181], v[104:107]
	v_mfma_f32_16x16x32_bf16 v[92:95], v[146:149], v[186:189], v[92:95]
	v_mfma_f32_16x16x32_bf16 v[88:91], v[162:165], v[186:189], v[88:91]
	v_mfma_f32_16x16x32_bf16 v[76:79], v[146:149], v[194:197], v[76:79]
	v_mfma_f32_16x16x32_bf16 v[72:75], v[162:165], v[194:197], v[72:75]
	v_mfma_f32_16x16x32_bf16 v[124:127], v[158:161], v[174:177], v[124:127]
	v_mfma_f32_16x16x32_bf16 v[120:123], v[166:169], v[174:177], v[120:123]
	v_mfma_f32_16x16x32_bf16 v[108:111], v[158:161], v[182:185], v[108:111]
	v_mfma_f32_16x16x32_bf16 v[104:107], v[166:169], v[182:185], v[104:107]
	v_mfma_f32_16x16x32_bf16 v[92:95], v[158:161], v[190:193], v[92:95]
	v_mfma_f32_16x16x32_bf16 v[88:91], v[166:169], v[190:193], v[88:91]
	v_mfma_f32_16x16x32_bf16 v[76:79], v[158:161], v[198:201], v[76:79]
	v_mfma_f32_16x16x32_bf16 v[72:75], v[166:169], v[198:201], v[72:75]
	v_mfma_f32_16x16x32_bf16 v[116:119], v[202:205], v[170:173], v[116:119]
	v_mfma_f32_16x16x32_bf16 v[112:115], v[210:213], v[170:173], v[112:115]
	v_mfma_f32_16x16x32_bf16 v[100:103], v[202:205], v[178:181], v[100:103]
	v_mfma_f32_16x16x32_bf16 v[96:99], v[210:213], v[178:181], v[96:99]
	v_mfma_f32_16x16x32_bf16 v[84:87], v[202:205], v[186:189], v[84:87]
	v_mfma_f32_16x16x32_bf16 v[80:83], v[210:213], v[186:189], v[80:83]
	v_mfma_f32_16x16x32_bf16 v[68:71], v[202:205], v[194:197], v[68:71]
	v_mfma_f32_16x16x32_bf16 v[64:67], v[210:213], v[194:197], v[64:67]
	v_mfma_f32_16x16x32_bf16 v[116:119], v[206:209], v[174:177], v[116:119]
	v_mfma_f32_16x16x32_bf16 v[112:115], v[214:217], v[174:177], v[112:115]
	v_mfma_f32_16x16x32_bf16 v[100:103], v[206:209], v[182:185], v[100:103]
	v_mfma_f32_16x16x32_bf16 v[96:99], v[214:217], v[182:185], v[96:99]
	v_mfma_f32_16x16x32_bf16 v[84:87], v[206:209], v[190:193], v[84:87]
	v_mfma_f32_16x16x32_bf16 v[80:83], v[214:217], v[190:193], v[80:83]
	v_mfma_f32_16x16x32_bf16 v[68:71], v[206:209], v[198:201], v[68:71]
	v_mfma_f32_16x16x32_bf16 v[64:67], v[214:217], v[198:201], v[64:67]
	s_barrier
	ds_read_b128 v[170:173], v155 offset:16384
	ds_read_b128 v[174:177], v155 offset:17408
	ds_read_b128 v[178:181], v155 offset:18432
	ds_read_b128 v[182:185], v155 offset:19456
	ds_read_b128 v[186:189], v155 offset:20480
	ds_read_b128 v[190:193], v155 offset:21504
	ds_read_b128 v[194:197], v155 offset:22528
	ds_read_b128 v[198:201], v155 offset:23552
	s_add_i32 s55, s78, s35
	s_mov_b32 m0, s55
	v_lshl_add_u64 v[218:219], s[64:65], 0, v[132:133]
	global_load_lds_dwordx4 v[218:219], off
	s_add_i32 m0, s55, 0x2000
	v_lshl_add_u64 v[220:221], s[64:65], 0, v[136:137]
	global_load_lds_dwordx4 v[220:221], off
	s_mov_b32 m0, s68
	v_lshl_add_u64 v[222:223], s[66:67], 0, v[130:131]
	global_load_lds_dwordx4 v[222:223], off
	s_mov_b32 m0, s69
	v_lshl_add_u64 v[224:225], s[66:67], 0, v[134:135]
	global_load_lds_dwordx4 v[224:225], off
	s_add_u32 s82, s64, 0x40000
	s_addc_u32 s83, s65, 0
	s_add_i32 s55, s79, s35
	s_mov_b32 m0, s55
	v_lshl_add_u64 v[240:241], s[82:83], 0, v[132:133]
	global_load_lds_dwordx4 v[240:241], off
	s_add_i32 m0, s55, 0x2000
	v_lshl_add_u64 v[240:241], s[82:83], 0, v[136:137]
	global_load_lds_dwordx4 v[240:241], off
	s_waitcnt vmcnt(8) lgkmcnt(0)
	s_barrier
; #define PG8_STAGE(bufoff, gbase, voff) do { _Pragma("unroll") for (int _i = 0; _i < 2; ++_i) \
;         __builtin_amdgcn_global_load_lds((const unsigned*)((const char*)(gbase) + (voff)[_i]), (LAS unsigned*)(lds + (bufoff) + ldsw + _i * 8192), 16, 0, 0); } while (0)
; #define PG8_LDA(dst, b, h) do { _Pragma("unroll") for (int m = 0; m < 4; ++m) _Pragma("unroll") for (int k = 0; k < 2; ++k) dst[m][k] = *(const LAS bf16x8*)(lds + PG8_SA(b, h) + aoff + m * 2048 + k * 1024); } while (0)
; #define PG8_LDB(dst, b, h) do { _Pragma("unroll") for (int n = 0; n < 2; ++n) _Pragma("unroll") for (int k = 0; k < 2; ++k) dst[n][k] = *(const LAS bf16x8*)(lds + PG8_SB(b, h) + boff + n * 2048 + k * 1024); } while (0)
; #define PG8_MMA(ai, bj, At, Bt) do { __builtin_amdgcn_s_setprio(1); _Pragma("unroll") for (int m = 0; m < 4; ++m) _Pragma("unroll") for (int n = 0; n < 2; ++n) _Pragma("unroll") for (int k = 0; k < 2; ++k) \
;         acc[ai][bj][m][n] = __builtin_amdgcn_mfma_f32_16x16x32_bf16(Bt[n][k], At[m][k], acc[ai][bj][m][n], 0, 0, 0); __builtin_amdgcn_s_setprio(0); } while (0)
; #define PG8_WAIT_V(n) asm volatile("s_waitcnt vmcnt(" #n ")" ::: "memory")
; #define PG8_WAIT_L(n) asm volatile("s_waitcnt lgkmcnt(" #n ")" ::: "memory")
; #define PG8_BAR __builtin_amdgcn_s_barrier()
; #define PG8_SCHED __builtin_amdgcn_sched_barrier(0)
; template <class Epi>
; __device__ __forceinline__ void gemm_phase(LAS unsigned char* lds, const Gemm g, const StaticOrder& S, const Epi& E) {
;     ...
;             PG8_BAR; PG8_WAIT_L(0); PG8_MMA(1, 0, At, B0); PG8_BAR; PG8_SCHED;
;             PG8_STAGE(PG8_SB(0, 1), b2 + hstepB, voffB);
;             PG8_WAIT_V(6); PG8_BAR; PG8_MMA(1, 1, At, B1); PG8_BAR;
;             PG8_LDB(B0, 1, 0); PG8_SCHED; PG8_LDA(At, 1, 0); PG8_STAGE(PG8_SA(0, 1), a2 + hstepA, voffA);
;             PG8_WAIT_L(8); PG8_BAR; PG8_WAIT_L(0); PG8_MMA(0, 0, At, B0); PG8_BAR; PG8_SCHED;
;             PG8_LDB(B1, 1, 1); PG8_STAGE(PG8_SB(1, 0), b3, voffB);
;             PG8_BAR; PG8_WAIT_L(0); PG8_MMA(0, 1, At, B1); PG8_BAR;
	v_mfma_f32_16x16x32_bf16 v[60:63], v[146:149], v[170:173], v[60:63]
	v_mfma_f32_16x16x32_bf16 v[56:59], v[162:165], v[170:173], v[56:59]
	v_mfma_f32_16x16x32_bf16 v[44:47], v[146:149], v[178:181], v[44:47]
	v_mfma_f32_16x16x32_bf16 v[40:43], v[162:165], v[178:181], v[40:43]
	v_mfma_f32_16x16x32_bf16 v[28:31], v[146:149], v[186:189], v[28:31]
	v_mfma_f32_16x16x32_bf16 v[24:27], v[162:165], v[186:189], v[24:27]
	v_mfma_f32_16x16x32_bf16 v[12:15], v[146:149], v[194:197], v[12:15]
	v_mfma_f32_16x16x32_bf16 v[8:11], v[162:165], v[194:197], v[8:11]
	v_mfma_f32_16x16x32_bf16 v[60:63], v[158:161], v[174:177], v[60:63]
	v_mfma_f32_16x16x32_bf16 v[56:59], v[166:169], v[174:177], v[56:59]
	v_mfma_f32_16x16x32_bf16 v[44:47], v[158:161], v[182:185], v[44:47]
	v_mfma_f32_16x16x32_bf16 v[40:43], v[166:169], v[182:185], v[40:43]
	v_mfma_f32_16x16x32_bf16 v[28:31], v[158:161], v[190:193], v[28:31]
	v_mfma_f32_16x16x32_bf16 v[24:27], v[166:169], v[190:193], v[24:27]
	v_mfma_f32_16x16x32_bf16 v[12:15], v[158:161], v[198:201], v[12:15]
	v_mfma_f32_16x16x32_bf16 v[8:11], v[166:169], v[198:201], v[8:11]
	v_mfma_f32_16x16x32_bf16 v[52:55], v[202:205], v[170:173], v[52:55]
	v_mfma_f32_16x16x32_bf16 v[48:51], v[210:213], v[170:173], v[48:51]
	v_mfma_f32_16x16x32_bf16 v[36:39], v[202:205], v[178:181], v[36:39]
	v_mfma_f32_16x16x32_bf16 v[32:35], v[210:213], v[178:181], v[32:35]
	v_mfma_f32_16x16x32_bf16 v[20:23], v[202:205], v[186:189], v[20:23]
	v_mfma_f32_16x16x32_bf16 v[16:19], v[210:213], v[186:189], v[16:19]
	v_mfma_f32_16x16x32_bf16 v[4:7], v[202:205], v[194:197], v[4:7]
	v_mfma_f32_16x16x32_bf16 v[0:3], v[210:213], v[194:197], v[0:3]
	v_mfma_f32_16x16x32_bf16 v[52:55], v[206:209], v[174:177], v[52:55]
	v_mfma_f32_16x16x32_bf16 v[48:51], v[214:217], v[174:177], v[48:51]
	v_mfma_f32_16x16x32_bf16 v[36:39], v[206:209], v[182:185], v[36:39]
	v_mfma_f32_16x16x32_bf16 v[32:35], v[214:217], v[182:185], v[32:35]
	v_mfma_f32_16x16x32_bf16 v[20:23], v[206:209], v[190:193], v[20:23]
	v_mfma_f32_16x16x32_bf16 v[16:19], v[214:217], v[190:193], v[16:19]
	v_mfma_f32_16x16x32_bf16 v[4:7], v[206:209], v[198:201], v[4:7]
	v_mfma_f32_16x16x32_bf16 v[0:3], v[214:217], v[198:201], v[0:3]
	s_barrier
	s_add_i32 s55, 0, 0x18000
	v_add_u32_e32 v157, s55, v152
	ds_read_b128 v[146:149], v157
	ds_read_b128 v[158:161], v157 offset:1024
	ds_read_b128 v[162:165], v157 offset:2048
	ds_read_b128 v[166:169], v157 offset:3072
	ds_read_b128 v[170:173], v155 offset:32768
	ds_read_b128 v[174:177], v155 offset:33792
	ds_read_b128 v[178:181], v155 offset:34816
	ds_read_b128 v[182:185], v155 offset:35840
	ds_read_b128 v[186:189], v155 offset:36864
	ds_read_b128 v[190:193], v155 offset:37888
	ds_read_b128 v[194:197], v155 offset:38912
	ds_read_b128 v[198:201], v155 offset:39936
	s_add_i32 s98, 0, 0x1c000
	v_add_u32_e32 v246, s98, v152
	ds_read_b128 v[202:205], v246
	ds_read_b128 v[206:209], v246 offset:1024
	ds_read_b128 v[210:213], v246 offset:2048
	ds_read_b128 v[214:217], v246 offset:3072
	s_add_u32 s66, s66, 0x40000
	s_addc_u32 s67, s67, 0
	s_mov_b32 m0, s70
	v_lshl_add_u64 v[244:245], s[66:67], 0, v[130:131]
	global_load_lds_dwordx4 v[244:245], off
	s_mov_b32 m0, s71
	v_lshl_add_u64 v[244:245], s[66:67], 0, v[134:135]
	global_load_lds_dwordx4 v[244:245], off
	s_waitcnt vmcnt(8) lgkmcnt(0)
	s_barrier
	v_mfma_f32_16x16x32_bf16 v[124:127], v[146:149], v[170:173], v[124:127]
	v_mfma_f32_16x16x32_bf16 v[120:123], v[162:165], v[170:173], v[120:123]
	v_mfma_f32_16x16x32_bf16 v[108:111], v[146:149], v[178:181], v[108:111]
	v_mfma_f32_16x16x32_bf16 v[104:107], v[162:165], v[178:181], v[104:107]
	v_mfma_f32_16x16x32_bf16 v[92:95], v[146:149], v[186:189], v[92:95]
	v_mfma_f32_16x16x32_bf16 v[88:91], v[162:165], v[186:189], v[88:91]
	v_mfma_f32_16x16x32_bf16 v[76:79], v[146:149], v[194:197], v[76:79]
	v_mfma_f32_16x16x32_bf16 v[72:75], v[162:165], v[194:197], v[72:75]
	v_mfma_f32_16x16x32_bf16 v[124:127], v[158:161], v[174:177], v[124:127]
	v_mfma_f32_16x16x32_bf16 v[120:123], v[166:169], v[174:177], v[120:123]
	v_mfma_f32_16x16x32_bf16 v[108:111], v[158:161], v[182:185], v[108:111]
	v_mfma_f32_16x16x32_bf16 v[104:107], v[166:169], v[182:185], v[104:107]
	v_mfma_f32_16x16x32_bf16 v[92:95], v[158:161], v[190:193], v[92:95]
	v_mfma_f32_16x16x32_bf16 v[88:91], v[166:169], v[190:193], v[88:91]
	v_mfma_f32_16x16x32_bf16 v[76:79], v[158:161], v[198:201], v[76:79]
	v_mfma_f32_16x16x32_bf16 v[72:75], v[166:169], v[198:201], v[72:75]
	v_mfma_f32_16x16x32_bf16 v[116:119], v[202:205], v[170:173], v[116:119]
	v_mfma_f32_16x16x32_bf16 v[112:115], v[210:213], v[170:173], v[112:115]
	v_mfma_f32_16x16x32_bf16 v[100:103], v[202:205], v[178:181], v[100:103]
	v_mfma_f32_16x16x32_bf16 v[96:99], v[210:213], v[178:181], v[96:99]
	v_mfma_f32_16x16x32_bf16 v[84:87], v[202:205], v[186:189], v[84:87]
	v_mfma_f32_16x16x32_bf16 v[80:83], v[210:213], v[186:189], v[80:83]
	v_mfma_f32_16x16x32_bf16 v[68:71], v[202:205], v[194:197], v[68:71]
	v_mfma_f32_16x16x32_bf16 v[64:67], v[210:213], v[194:197], v[64:67]
	v_mfma_f32_16x16x32_bf16 v[116:119], v[206:209], v[174:177], v[116:119]
	v_mfma_f32_16x16x32_bf16 v[112:115], v[214:217], v[174:177], v[112:115]
	v_mfma_f32_16x16x32_bf16 v[100:103], v[206:209], v[182:185], v[100:103]
	v_mfma_f32_16x16x32_bf16 v[96:99], v[214:217], v[182:185], v[96:99]
	v_mfma_f32_16x16x32_bf16 v[84:87], v[206:209], v[190:193], v[84:87]
	v_mfma_f32_16x16x32_bf16 v[80:83], v[214:217], v[190:193], v[80:83]
	v_mfma_f32_16x16x32_bf16 v[68:71], v[206:209], v[198:201], v[68:71]
	v_mfma_f32_16x16x32_bf16 v[64:67], v[214:217], v[198:201], v[64:67]
	s_barrier
; __device__ __forceinline__ float gelu_t(float x) { return x * __builtin_amdgcn_rcpf(1.f + __expf(-1.5957691216057308f * (x + 0.044715f * x * x * x))); }
; #define PG8_STAGE(bufoff, gbase, voff) do { _Pragma("unroll") for (int _i = 0; _i < 2; ++_i) \
;         __builtin_amdgcn_global_load_lds((const unsigned*)((const char*)(gbase) + (voff)[_i]), (LAS unsigned*)(lds + (bufoff) + ldsw + _i * 8192), 16, 0, 0); } while (0)
; #define PG8_LDA(dst, b, h) do { _Pragma("unroll") for (int m = 0; m < 4; ++m) _Pragma("unroll") for (int k = 0; k < 2; ++k) dst[m][k] = *(const LAS bf16x8*)(lds + PG8_SA(b, h) + aoff + m * 2048 + k * 1024); } while (0)
; #define PG8_MMA(ai, bj, At, Bt) do { __builtin_amdgcn_s_setprio(1); _Pragma("unroll") for (int m = 0; m < 4; ++m) _Pragma("unroll") for (int n = 0; n < 2; ++n) _Pragma("unroll") for (int k = 0; k < 2; ++k) \
;         acc[ai][bj][m][n] = __builtin_amdgcn_mfma_f32_16x16x32_bf16(Bt[n][k], At[m][k], acc[ai][bj][m][n], 0, 0, 0); __builtin_amdgcn_s_setprio(0); } while (0)
; #define PG8_WAIT_V(n) asm volatile("s_waitcnt vmcnt(" #n ")" ::: "memory")
; #define PG8_WAIT_L(n) asm volatile("s_waitcnt lgkmcnt(" #n ")" ::: "memory")
; #define PG8_BAR __builtin_amdgcn_s_barrier()
; #define PG8_SCHED __builtin_amdgcn_sched_barrier(0)
;     __device__ __forceinline__ void operator()(const f32x4 (&acc)[2][2][4][2], const Unit& u, int wr, int wc, int fr, int fq) const {
;     ...
; #pragma unroll
;         for (int ai = 0; ai < 2; ++ai)
; #pragma unroll
;             for (int m = 0; m < 4; ++m) { const int row = row0 + ai * HALF + m * 16; u16* rowp = O + (size_t)row * ldc + col0;
; #pragma unroll
;                 for (int bj = 0; bj < 2; ++bj) { f32x4 v0 = acc[ai][bj][m][0], v1 = acc[ai][bj][m][1];
;                     if (col0 + bj * HALF >= gelu_from) { v0 = (f32x4){gelu_t(v0.x), gelu_t(v0.y), gelu_t(v0.z), gelu_t(v0.w)}; v1 = (f32x4){gelu_t(v1.x), gelu_t(v1.y), gelu_t(v1.z), gelu_t(v1.w)}; }
; template <class Epi>
; __device__ __forceinline__ void gemm_phase(LAS unsigned char* lds, const Gemm g, const StaticOrder& S, const Epi& E) {
;     ...
;             PG8_LDA(At, 1, 1); PG8_STAGE(PG8_SA(1, 0), a3, voffA);
;             PG8_BAR; PG8_WAIT_L(0); PG8_MMA(1, 0, At, B0); PG8_BAR; PG8_SCHED;
;             PG8_STAGE(PG8_SB(1, 1), b3 + hstepB, voffB);
;             PG8_WAIT_V(6); PG8_BAR; PG8_MMA(1, 1, At, B1); PG8_BAR;
	ds_read_b128 v[170:173], v155 offset:49152
	ds_read_b128 v[174:177], v155 offset:50176
	ds_read_b128 v[178:181], v155 offset:51200
	ds_read_b128 v[182:185], v155 offset:52224
	ds_read_b128 v[186:189], v155 offset:53248
	ds_read_b128 v[190:193], v155 offset:54272
	ds_read_b128 v[194:197], v155 offset:55296
	ds_read_b128 v[198:201], v155 offset:56320
	s_add_i32 s55, s55, s35
	s_mov_b32 m0, s55
	v_lshl_add_u64 v[218:219], v[218:219], 0, s[28:29]
	global_load_lds_dwordx4 v[218:219], off
	s_add_i32 m0, s55, 0x2000
	v_lshl_add_u64 v[218:219], v[220:221], 0, s[28:29]
	global_load_lds_dwordx4 v[218:219], off
	s_mov_b32 m0, s73
	v_lshl_add_u64 v[218:219], v[222:223], 0, s[28:29]
	global_load_lds_dwordx4 v[218:219], off
	s_mov_b32 m0, s74
	v_lshl_add_u64 v[218:219], v[224:225], 0, s[28:29]
	global_load_lds_dwordx4 v[218:219], off
	s_add_u32 s64, s64, 0x40080
	s_addc_u32 s65, s65, 0
	s_add_i32 s55, s98, s35
	s_mov_b32 m0, s55
	v_lshl_add_u64 v[240:241], s[64:65], 0, v[132:133]
	global_load_lds_dwordx4 v[240:241], off
	s_add_i32 m0, s55, 0x2000
	v_lshl_add_u64 v[240:241], s[64:65], 0, v[136:137]
	global_load_lds_dwordx4 v[240:241], off
	s_waitcnt vmcnt(8) lgkmcnt(0)
	s_barrier
	v_mfma_f32_16x16x32_bf16 v[60:63], v[146:149], v[170:173], v[60:63]
	v_mfma_f32_16x16x32_bf16 v[56:59], v[162:165], v[170:173], v[56:59]
	v_mfma_f32_16x16x32_bf16 v[44:47], v[146:149], v[178:181], v[44:47]
	v_mfma_f32_16x16x32_bf16 v[40:43], v[162:165], v[178:181], v[40:43]
	v_mfma_f32_16x16x32_bf16 v[28:31], v[146:149], v[186:189], v[28:31]
	v_mfma_f32_16x16x32_bf16 v[24:27], v[162:165], v[186:189], v[24:27]
	v_mfma_f32_16x16x32_bf16 v[12:15], v[146:149], v[194:197], v[12:15]
	v_mfma_f32_16x16x32_bf16 v[8:11], v[162:165], v[194:197], v[8:11]
	v_mfma_f32_16x16x32_bf16 v[60:63], v[158:161], v[174:177], v[60:63]
	v_mfma_f32_16x16x32_bf16 v[56:59], v[166:169], v[174:177], v[56:59]
	v_mfma_f32_16x16x32_bf16 v[44:47], v[158:161], v[182:185], v[44:47]
	v_mfma_f32_16x16x32_bf16 v[40:43], v[166:169], v[182:185], v[40:43]
	v_mfma_f32_16x16x32_bf16 v[28:31], v[158:161], v[190:193], v[28:31]
	v_mfma_f32_16x16x32_bf16 v[24:27], v[166:169], v[190:193], v[24:27]
	v_mfma_f32_16x16x32_bf16 v[12:15], v[158:161], v[198:201], v[12:15]
	v_mfma_f32_16x16x32_bf16 v[8:11], v[166:169], v[198:201], v[8:11]
	v_mfma_f32_16x16x32_bf16 v[52:55], v[202:205], v[170:173], v[52:55]
	v_mfma_f32_16x16x32_bf16 v[48:51], v[210:213], v[170:173], v[48:51]
	v_mfma_f32_16x16x32_bf16 v[36:39], v[202:205], v[178:181], v[36:39]
	v_mfma_f32_16x16x32_bf16 v[32:35], v[210:213], v[178:181], v[32:35]
	v_mfma_f32_16x16x32_bf16 v[20:23], v[202:205], v[186:189], v[20:23]
	v_mfma_f32_16x16x32_bf16 v[16:19], v[210:213], v[186:189], v[16:19]
	v_mfma_f32_16x16x32_bf16 v[4:7], v[202:205], v[194:197], v[4:7]
	v_mfma_f32_16x16x32_bf16 v[0:3], v[210:213], v[194:197], v[0:3]
	v_mfma_f32_16x16x32_bf16 v[52:55], v[206:209], v[174:177], v[52:55]
	v_mfma_f32_16x16x32_bf16 v[48:51], v[214:217], v[174:177], v[48:51]
	v_mfma_f32_16x16x32_bf16 v[36:39], v[206:209], v[182:185], v[36:39]
	v_mfma_f32_16x16x32_bf16 v[32:35], v[214:217], v[182:185], v[32:35]
	v_mfma_f32_16x16x32_bf16 v[20:23], v[206:209], v[190:193], v[20:23]
	v_mfma_f32_16x16x32_bf16 v[16:19], v[214:217], v[190:193], v[16:19]
	v_mfma_f32_16x16x32_bf16 v[4:7], v[206:209], v[198:201], v[4:7]
	v_mfma_f32_16x16x32_bf16 v[0:3], v[214:217], v[198:201], v[0:3]
	s_add_i32 s33, s33, 2
	s_add_u32 s62, s62, 0x100
	s_addc_u32 s63, s63, 0
	s_add_u32 s9, s9, 0x100
	s_addc_u32 s31, s31, 0
	s_cmp_gt_u32 s33, 13
	s_barrier
	s_cbranch_scc0 .LBB0_119
	v_lshl_or_b32 v146, s60, 8, v153
	v_cmp_lt_i32_e32 vcc, s80, v146
	s_and_saveexec_b64 s[60:61], vcc
	s_cbranch_execz .LBB0_122
	v_mul_f32_e32 v148, 0x3d372713, v125
	v_mul_f32_e32 v148, v125, v148
	v_fma_f32 v148, v125, v148, v125
	v_mul_f32_e32 v147, 0x3d372713, v124
	v_mul_f32_e32 v148, 0xbfcc422a, v148
	v_mul_f32_e32 v147, v124, v147
	v_mul_f32_e32 v148, 0x3fb8aa3b, v148
	v_fma_f32 v147, v124, v147, v124
	v_exp_f32_e32 v149, v148
	v_mul_f32_e32 v148, 0x3d372713, v126
	v_mul_f32_e32 v147, 0xbfcc422a, v147
	v_mul_f32_e32 v148, v126, v148
	v_mul_f32_e32 v147, 0x3fb8aa3b, v147
	v_fma_f32 v148, v126, v148, v126
	v_exp_f32_e32 v147, v147
	v_mul_f32_e32 v148, 0xbfcc422a, v148
	v_mul_f32_e32 v148, 0x3fb8aa3b, v148
	v_exp_f32_e32 v157, v148
	v_add_f32_e32 v147, 1.0, v147
	v_rcp_f32_e32 v148, v147
	v_add_f32_e32 v147, 1.0, v149
	v_rcp_f32_e32 v149, v147
	v_add_f32_e32 v147, 1.0, v157
	v_mul_f32_e32 v157, 0x3d372713, v127
	v_mul_f32_e32 v157, v127, v157
	v_mul_f32_e32 v158, 0x3d372713, v120
	v_fma_f32 v157, v127, v157, v127
	v_mul_f32_e32 v158, v120, v158
	v_mul_f32_e32 v157, 0xbfcc422a, v157
	v_fma_f32 v158, v120, v158, v120
	v_mul_f32_e32 v157, 0x3fb8aa3b, v157
	v_mul_f32_e32 v158, 0xbfcc422a, v158
	v_exp_f32_e32 v157, v157
	v_mul_f32_e32 v158, 0x3fb8aa3b, v158
	v_exp_f32_e32 v160, v158
	v_rcp_f32_e32 v158, v147
	v_add_f32_e32 v147, 1.0, v157
	v_rcp_f32_e32 v159, v147
	v_add_f32_e32 v147, 1.0, v160
	v_mul_f32_e32 v157, 0x3d372713, v122
	v_rcp_f32_e32 v160, v147
	v_mul_f32_e32 v147, 0x3d372713, v121
	v_mul_f32_e32 v157, v122, v157
	v_mul_f32_e32 v161, 0x3d372713, v123
	v_mul_f32_e32 v147, v121, v147
	v_fma_f32 v157, v122, v157, v122
	v_mul_f32_e32 v161, v123, v161
	v_fma_f32 v147, v121, v147, v121
	v_mul_f32_e32 v157, 0xbfcc422a, v157
	v_fma_f32 v161, v123, v161, v123
	v_mul_f32_e32 v147, 0xbfcc422a, v147
	v_mul_f32_e32 v157, 0x3fb8aa3b, v157
	v_mul_f32_e32 v161, 0xbfcc422a, v161
	v_mul_f32_e32 v147, 0x3fb8aa3b, v147
	v_exp_f32_e32 v157, v157
	v_mul_f32_e32 v161, 0x3fb8aa3b, v161
	v_exp_f32_e32 v147, v147
	v_exp_f32_e32 v161, v161
	v_add_f32_e32 v157, 1.0, v157
	v_rcp_f32_e32 v162, v157
	v_add_f32_e32 v147, 1.0, v147
	v_add_f32_e32 v157, 1.0, v161
	v_rcp_f32_e32 v163, v157
	v_rcp_f32_e32 v161, v147
	v_pk_mul_f32 v[126:127], v[126:127], v[158:159]
	v_pk_mul_f32 v[124:125], v[124:125], v[148:149]
	v_pk_mul_f32 v[122:123], v[122:123], v[162:163]
	v_pk_mul_f32 v[120:121], v[120:121], v[160:161]

; #define PG8_STAGE(bufoff, gbase, voff) do { _Pragma("unroll") for (int _i = 0; _i < 2; ++_i) \
;         __builtin_amdgcn_global_load_lds((const unsigned*)((const char*)(gbase) + (voff)[_i]), (LAS unsigned*)(lds + (bufoff) + ldsw + _i * 8192), 16, 0, 0); } while (0)
; #define PG8_LDA(dst, b, h) do { _Pragma("unroll") for (int m = 0; m < 4; ++m) _Pragma("unroll") for (int k = 0; k < 2; ++k) dst[m][k] = *(const LAS bf16x8*)(lds + PG8_SA(b, h) + aoff + m * 2048 + k * 1024); } while (0)
; #define PG8_LDB(dst, b, h) do { _Pragma("unroll") for (int n = 0; n < 2; ++n) _Pragma("unroll") for (int k = 0; k < 2; ++k) dst[n][k] = *(const LAS bf16x8*)(lds + PG8_SB(b, h) + boff + n * 2048 + k * 1024); } while (0)
; #define PG8_WAIT_V(n) asm volatile("s_waitcnt vmcnt(" #n ")" ::: "memory")
; #define PG8_WAIT_L(n) asm volatile("s_waitcnt lgkmcnt(" #n ")" ::: "memory")
; #define PG8_BAR __builtin_amdgcn_s_barrier()
; #define PG8_SCHED __builtin_amdgcn_sched_barrier(0)
; template <class Epi>
; __device__ __forceinline__ void gemm_phase(LAS unsigned char* lds, const Gemm g, const StaticOrder& S, const Epi& E) {
;     ...
;         const bool has_next = S.next(ui + 1, nxt);
;         const char* nA = has_next ? (const char*)g.A + (size_t)nxt.pm * tstepA + (size_t)nxt.kt0 * kstep : cA; const char* nB = has_next ? (const char*)g.Bt + (size_t)nxt.pn * tstepB + (size_t)nxt.kt0 * kstep : cB;
;         const int nt = cur.nkt;
;         for (int t = 0; t < nt; t += 2) {
;             const bool last = (t == nt - 2);
;             const char* a1 = cA + (size_t)(t + 1) * kstep;
;             const char* a2 = last ? nA : cA + (size_t)(t + 2) * kstep; const char* b2 = last ? nB : cB + (size_t)(t + 2) * kstep;
;             const char* a3 = a2 + kstep; const char* b3 = b2 + kstep;
;             PG8_LDB(B0, 0, 0); PG8_SCHED; PG8_LDA(At, 0, 0); PG8_STAGE(PG8_SA(1, 1), a1 + hstepA, voffA);
;             PG8_WAIT_L(8); PG8_BAR; PG8_WAIT_L(0); PG8_MMA(0, 0, At, B0); PG8_BAR; PG8_SCHED;
;             PG8_LDB(B1, 0, 1); PG8_STAGE(PG8_SB(0, 0), b2, voffB);
;             PG8_BAR; PG8_WAIT_L(0); PG8_MMA(0, 1, At, B1); PG8_BAR;
;             PG8_LDA(At, 0, 1); PG8_STAGE(PG8_SA(0, 0), a2, voffA);
;             PG8_BAR; PG8_WAIT_L(0); PG8_MMA(1, 0, At, B0); PG8_BAR; PG8_SCHED;
;             PG8_STAGE(PG8_SB(0, 1), b2 + hstepB, voffB);
;             PG8_WAIT_V(6); PG8_BAR; PG8_MMA(1, 1, At, B1); PG8_BAR;
.LBB0_456:
	s_add_i32 s85, s59, 2
	s_add_u32 s66, s64, 0xfffc0080
	s_addc_u32 s67, s65, -1
	s_cmp_eq_u32 s21, s59
	s_cselect_b32 s69, s63, s67
	s_cselect_b32 s68, s62, s66
	s_cselect_b32 s67, s1, s57
	s_cselect_b32 s66, s0, s31
	ds_read_b128 v[144:147], v158
	ds_read_b128 v[148:151], v158 offset:1024
	ds_read_b128 v[162:165], v158 offset:2048
	ds_read_b128 v[166:169], v158 offset:3072
	ds_read_b128 v[170:173], v159
	ds_read_b128 v[174:177], v159 offset:1024
	ds_read_b128 v[178:181], v159 offset:2048
	ds_read_b128 v[182:185], v159 offset:3072
	ds_read_b128 v[186:189], v159 offset:4096
	ds_read_b128 v[190:193], v159 offset:5120
	ds_read_b128 v[194:197], v159 offset:6144
	ds_read_b128 v[198:201], v159 offset:7168
	ds_read_b128 v[202:205], v160
	ds_read_b128 v[206:209], v160 offset:1024
	ds_read_b128 v[210:213], v160 offset:2048
	ds_read_b128 v[214:217], v160 offset:3072
	s_add_i32 m0, s35, 0xc000
	v_lshl_add_u64 v[152:153], s[64:65], 0, v[138:139]
	global_load_lds_dwordx4 v[152:153], off
	s_add_i32 m0, s35, 0xe000
	v_lshl_add_u64 v[152:153], s[64:65], 0, v[140:141]
	global_load_lds_dwordx4 v[152:153], off
	s_waitcnt vmcnt(8) lgkmcnt(0)
	s_barrier
	v_mfma_f32_16x16x32_bf16 v[124:127], v[144:147], v[170:173], v[124:127]
	v_mfma_f32_16x16x32_bf16 v[120:123], v[162:165], v[170:173], v[120:123]
	v_mfma_f32_16x16x32_bf16 v[116:119], v[144:147], v[178:181], v[116:119]
	v_mfma_f32_16x16x32_bf16 v[108:111], v[162:165], v[178:181], v[108:111]
	v_mfma_f32_16x16x32_bf16 v[100:103], v[144:147], v[186:189], v[100:103]
	v_mfma_f32_16x16x32_bf16 v[92:95], v[162:165], v[186:189], v[92:95]
	v_mfma_f32_16x16x32_bf16 v[84:87], v[144:147], v[194:197], v[84:87]
	v_mfma_f32_16x16x32_bf16 v[76:79], v[162:165], v[194:197], v[76:79]
	v_mfma_f32_16x16x32_bf16 v[124:127], v[148:151], v[174:177], v[124:127]
	v_mfma_f32_16x16x32_bf16 v[120:123], v[166:169], v[174:177], v[120:123]
	v_mfma_f32_16x16x32_bf16 v[116:119], v[148:151], v[182:185], v[116:119]
	v_mfma_f32_16x16x32_bf16 v[108:111], v[166:169], v[182:185], v[108:111]
	v_mfma_f32_16x16x32_bf16 v[100:103], v[148:151], v[190:193], v[100:103]
	v_mfma_f32_16x16x32_bf16 v[92:95], v[166:169], v[190:193], v[92:95]
	v_mfma_f32_16x16x32_bf16 v[84:87], v[148:151], v[198:201], v[84:87]
	v_mfma_f32_16x16x32_bf16 v[76:79], v[166:169], v[198:201], v[76:79]
	v_mfma_f32_16x16x32_bf16 v[112:115], v[202:205], v[170:173], v[112:115]
	v_mfma_f32_16x16x32_bf16 v[104:107], v[210:213], v[170:173], v[104:107]
	v_mfma_f32_16x16x32_bf16 v[96:99], v[202:205], v[178:181], v[96:99]
	v_mfma_f32_16x16x32_bf16 v[88:91], v[210:213], v[178:181], v[88:91]
	v_mfma_f32_16x16x32_bf16 v[80:83], v[202:205], v[186:189], v[80:83]
	v_mfma_f32_16x16x32_bf16 v[72:75], v[210:213], v[186:189], v[72:75]
	v_mfma_f32_16x16x32_bf16 v[68:71], v[202:205], v[194:197], v[68:71]
	v_mfma_f32_16x16x32_bf16 v[64:67], v[210:213], v[194:197], v[64:67]
	v_mfma_f32_16x16x32_bf16 v[112:115], v[206:209], v[174:177], v[112:115]
	v_mfma_f32_16x16x32_bf16 v[104:107], v[214:217], v[174:177], v[104:107]
	v_mfma_f32_16x16x32_bf16 v[96:99], v[206:209], v[182:185], v[96:99]
	v_mfma_f32_16x16x32_bf16 v[88:91], v[214:217], v[182:185], v[88:91]
	v_mfma_f32_16x16x32_bf16 v[80:83], v[206:209], v[190:193], v[80:83]
	v_mfma_f32_16x16x32_bf16 v[72:75], v[214:217], v[190:193], v[72:75]
	v_mfma_f32_16x16x32_bf16 v[68:71], v[206:209], v[198:201], v[68:71]
	v_mfma_f32_16x16x32_bf16 v[64:67], v[214:217], v[198:201], v[64:67]
	s_barrier
	ds_read_b128 v[170:173], v159 offset:16384
	ds_read_b128 v[174:177], v159 offset:17408
	ds_read_b128 v[178:181], v159 offset:18432
	ds_read_b128 v[182:185], v159 offset:19456
	ds_read_b128 v[186:189], v159 offset:20480
	ds_read_b128 v[190:193], v159 offset:21504
	ds_read_b128 v[194:197], v159 offset:22528
	ds_read_b128 v[198:201], v159 offset:23552
	s_add_i32 s59, s78, s33
	s_mov_b32 m0, s59
	v_lshl_add_u64 v[152:153], s[66:67], 0, v[132:133]
	global_load_lds_dwordx4 v[152:153], off
	s_add_i32 m0, s59, 0x2000
	v_lshl_add_u64 v[218:219], s[66:67], 0, v[136:137]
	global_load_lds_dwordx4 v[218:219], off
	s_mov_b32 m0, s35
	v_lshl_add_u64 v[220:221], s[68:69], 0, v[130:131]
	global_load_lds_dwordx4 v[220:221], off
	s_mov_b32 m0, s70
	v_lshl_add_u64 v[222:223], s[68:69], 0, v[134:135]
	global_load_lds_dwordx4 v[222:223], off
	s_add_u32 s86, s66, 0x40000
	s_addc_u32 s87, s67, 0
	s_add_i32 s59, s79, s33
	s_mov_b32 m0, s59
	v_lshl_add_u64 v[240:241], s[86:87], 0, v[132:133]
	global_load_lds_dwordx4 v[240:241], off
	s_add_i32 m0, s59, 0x2000
	v_lshl_add_u64 v[240:241], s[86:87], 0, v[136:137]
	global_load_lds_dwordx4 v[240:241], off
	s_waitcnt vmcnt(8) lgkmcnt(0)
	s_barrier
; #define PG8_STAGE(bufoff, gbase, voff) do { _Pragma("unroll") for (int _i = 0; _i < 2; ++_i) \
;         __builtin_amdgcn_global_load_lds((const unsigned*)((const char*)(gbase) + (voff)[_i]), (LAS unsigned*)(lds + (bufoff) + ldsw + _i * 8192), 16, 0, 0); } while (0)
; #define PG8_LDA(dst, b, h) do { _Pragma("unroll") for (int m = 0; m < 4; ++m) _Pragma("unroll") for (int k = 0; k < 2; ++k) dst[m][k] = *(const LAS bf16x8*)(lds + PG8_SA(b, h) + aoff + m * 2048 + k * 1024); } while (0)
; #define PG8_LDB(dst, b, h) do { _Pragma("unroll") for (int n = 0; n < 2; ++n) _Pragma("unroll") for (int k = 0; k < 2; ++k) dst[n][k] = *(const LAS bf16x8*)(lds + PG8_SB(b, h) + boff + n * 2048 + k * 1024); } while (0)
; #define PG8_MMA(ai, bj, At, Bt) do { __builtin_amdgcn_s_setprio(1); _Pragma("unroll") for (int m = 0; m < 4; ++m) _Pragma("unroll") for (int n = 0; n < 2; ++n) _Pragma("unroll") for (int k = 0; k < 2; ++k) \
;         acc[ai][bj][m][n] = __builtin_amdgcn_mfma_f32_16x16x32_bf16(Bt[n][k], At[m][k], acc[ai][bj][m][n], 0, 0, 0); __builtin_amdgcn_s_setprio(0); } while (0)
; #define PG8_WAIT_V(n) asm volatile("s_waitcnt vmcnt(" #n ")" ::: "memory")
; #define PG8_WAIT_L(n) asm volatile("s_waitcnt lgkmcnt(" #n ")" ::: "memory")
; #define PG8_BAR __builtin_amdgcn_s_barrier()
; #define PG8_SCHED __builtin_amdgcn_sched_barrier(0)
; template <class Epi>
; __device__ __forceinline__ void gemm_phase(LAS unsigned char* lds, const Gemm g, const StaticOrder& S, const Epi& E) {
;     ...
;             PG8_BAR; PG8_WAIT_L(0); PG8_MMA(1, 0, At, B0); PG8_BAR; PG8_SCHED;
;             PG8_STAGE(PG8_SB(0, 1), b2 + hstepB, voffB);
;             PG8_WAIT_V(6); PG8_BAR; PG8_MMA(1, 1, At, B1); PG8_BAR;
;             PG8_LDB(B0, 1, 0); PG8_SCHED; PG8_LDA(At, 1, 0); PG8_STAGE(PG8_SA(0, 1), a2 + hstepA, voffA);
;             PG8_WAIT_L(8); PG8_BAR; PG8_WAIT_L(0); PG8_MMA(0, 0, At, B0); PG8_BAR; PG8_SCHED;
;             PG8_LDB(B1, 1, 1); PG8_STAGE(PG8_SB(1, 0), b3, voffB);
;             PG8_BAR; PG8_WAIT_L(0); PG8_MMA(0, 1, At, B1); PG8_BAR;
	v_mfma_f32_16x16x32_bf16 v[60:63], v[144:147], v[170:173], v[60:63]
	v_mfma_f32_16x16x32_bf16 v[56:59], v[162:165], v[170:173], v[56:59]
	v_mfma_f32_16x16x32_bf16 v[52:55], v[144:147], v[178:181], v[52:55]
	v_mfma_f32_16x16x32_bf16 v[44:47], v[162:165], v[178:181], v[44:47]
	v_mfma_f32_16x16x32_bf16 v[36:39], v[144:147], v[186:189], v[36:39]
	v_mfma_f32_16x16x32_bf16 v[28:31], v[162:165], v[186:189], v[28:31]
	v_mfma_f32_16x16x32_bf16 v[20:23], v[144:147], v[194:197], v[20:23]
	v_mfma_f32_16x16x32_bf16 v[12:15], v[162:165], v[194:197], v[12:15]
	v_mfma_f32_16x16x32_bf16 v[60:63], v[148:151], v[174:177], v[60:63]
	v_mfma_f32_16x16x32_bf16 v[56:59], v[166:169], v[174:177], v[56:59]
	v_mfma_f32_16x16x32_bf16 v[52:55], v[148:151], v[182:185], v[52:55]
	v_mfma_f32_16x16x32_bf16 v[44:47], v[166:169], v[182:185], v[44:47]
	v_mfma_f32_16x16x32_bf16 v[36:39], v[148:151], v[190:193], v[36:39]
	v_mfma_f32_16x16x32_bf16 v[28:31], v[166:169], v[190:193], v[28:31]
	v_mfma_f32_16x16x32_bf16 v[20:23], v[148:151], v[198:201], v[20:23]
	v_mfma_f32_16x16x32_bf16 v[12:15], v[166:169], v[198:201], v[12:15]
	v_mfma_f32_16x16x32_bf16 v[48:51], v[202:205], v[170:173], v[48:51]
	v_mfma_f32_16x16x32_bf16 v[40:43], v[210:213], v[170:173], v[40:43]
	v_mfma_f32_16x16x32_bf16 v[32:35], v[202:205], v[178:181], v[32:35]
	v_mfma_f32_16x16x32_bf16 v[24:27], v[210:213], v[178:181], v[24:27]
	v_mfma_f32_16x16x32_bf16 v[16:19], v[202:205], v[186:189], v[16:19]
	v_mfma_f32_16x16x32_bf16 v[8:11], v[210:213], v[186:189], v[8:11]
	v_mfma_f32_16x16x32_bf16 v[4:7], v[202:205], v[194:197], v[4:7]
	v_mfma_f32_16x16x32_bf16 v[0:3], v[210:213], v[194:197], v[0:3]
	v_mfma_f32_16x16x32_bf16 v[48:51], v[206:209], v[174:177], v[48:51]
	v_mfma_f32_16x16x32_bf16 v[40:43], v[214:217], v[174:177], v[40:43]
	v_mfma_f32_16x16x32_bf16 v[32:35], v[206:209], v[182:185], v[32:35]
	v_mfma_f32_16x16x32_bf16 v[24:27], v[214:217], v[182:185], v[24:27]
	v_mfma_f32_16x16x32_bf16 v[16:19], v[206:209], v[190:193], v[16:19]
	v_mfma_f32_16x16x32_bf16 v[8:11], v[214:217], v[190:193], v[8:11]
	v_mfma_f32_16x16x32_bf16 v[4:7], v[206:209], v[198:201], v[4:7]
	v_mfma_f32_16x16x32_bf16 v[0:3], v[214:217], v[198:201], v[0:3]
	s_barrier
	s_add_i32 s59, 0, 0x18000
	v_add_u32_e32 v161, s59, v156
	ds_read_b128 v[144:147], v161
	ds_read_b128 v[148:151], v161 offset:1024
	ds_read_b128 v[162:165], v161 offset:2048
	ds_read_b128 v[166:169], v161 offset:3072
	ds_read_b128 v[170:173], v159 offset:32768
	ds_read_b128 v[174:177], v159 offset:33792
	ds_read_b128 v[178:181], v159 offset:34816
	ds_read_b128 v[182:185], v159 offset:35840
	ds_read_b128 v[186:189], v159 offset:36864
	ds_read_b128 v[190:193], v159 offset:37888
	ds_read_b128 v[194:197], v159 offset:38912
	ds_read_b128 v[198:201], v159 offset:39936
	s_add_i32 s98, 0, 0x1c000
	v_add_u32_e32 v246, s98, v156
	ds_read_b128 v[202:205], v246
	ds_read_b128 v[206:209], v246 offset:1024
	ds_read_b128 v[210:213], v246 offset:2048
	ds_read_b128 v[214:217], v246 offset:3072
	s_add_u32 s68, s68, 0x40000
	s_addc_u32 s69, s69, 0
	s_mov_b32 m0, s71
	v_lshl_add_u64 v[244:245], s[68:69], 0, v[130:131]
	global_load_lds_dwordx4 v[244:245], off
	s_mov_b32 m0, s72
	v_lshl_add_u64 v[244:245], s[68:69], 0, v[134:135]
	global_load_lds_dwordx4 v[244:245], off
	s_waitcnt vmcnt(8) lgkmcnt(0)
	s_barrier
	v_mfma_f32_16x16x32_bf16 v[124:127], v[144:147], v[170:173], v[124:127]
	v_mfma_f32_16x16x32_bf16 v[120:123], v[162:165], v[170:173], v[120:123]
	v_mfma_f32_16x16x32_bf16 v[116:119], v[144:147], v[178:181], v[116:119]
	v_mfma_f32_16x16x32_bf16 v[108:111], v[162:165], v[178:181], v[108:111]
	v_mfma_f32_16x16x32_bf16 v[100:103], v[144:147], v[186:189], v[100:103]
	v_mfma_f32_16x16x32_bf16 v[92:95], v[162:165], v[186:189], v[92:95]
	v_mfma_f32_16x16x32_bf16 v[84:87], v[144:147], v[194:197], v[84:87]
	v_mfma_f32_16x16x32_bf16 v[76:79], v[162:165], v[194:197], v[76:79]
	v_mfma_f32_16x16x32_bf16 v[124:127], v[148:151], v[174:177], v[124:127]
	v_mfma_f32_16x16x32_bf16 v[120:123], v[166:169], v[174:177], v[120:123]
	v_mfma_f32_16x16x32_bf16 v[116:119], v[148:151], v[182:185], v[116:119]
	v_mfma_f32_16x16x32_bf16 v[108:111], v[166:169], v[182:185], v[108:111]
	v_mfma_f32_16x16x32_bf16 v[100:103], v[148:151], v[190:193], v[100:103]
	v_mfma_f32_16x16x32_bf16 v[92:95], v[166:169], v[190:193], v[92:95]
	v_mfma_f32_16x16x32_bf16 v[84:87], v[148:151], v[198:201], v[84:87]
	v_mfma_f32_16x16x32_bf16 v[76:79], v[166:169], v[198:201], v[76:79]
	v_mfma_f32_16x16x32_bf16 v[112:115], v[202:205], v[170:173], v[112:115]
	v_mfma_f32_16x16x32_bf16 v[104:107], v[210:213], v[170:173], v[104:107]
	v_mfma_f32_16x16x32_bf16 v[96:99], v[202:205], v[178:181], v[96:99]
	v_mfma_f32_16x16x32_bf16 v[88:91], v[210:213], v[178:181], v[88:91]
	v_mfma_f32_16x16x32_bf16 v[80:83], v[202:205], v[186:189], v[80:83]
	v_mfma_f32_16x16x32_bf16 v[72:75], v[210:213], v[186:189], v[72:75]
	v_mfma_f32_16x16x32_bf16 v[68:71], v[202:205], v[194:197], v[68:71]
	v_mfma_f32_16x16x32_bf16 v[64:67], v[210:213], v[194:197], v[64:67]
	v_mfma_f32_16x16x32_bf16 v[112:115], v[206:209], v[174:177], v[112:115]
	v_mfma_f32_16x16x32_bf16 v[104:107], v[214:217], v[174:177], v[104:107]
	v_mfma_f32_16x16x32_bf16 v[96:99], v[206:209], v[182:185], v[96:99]
	v_mfma_f32_16x16x32_bf16 v[88:91], v[214:217], v[182:185], v[88:91]
	v_mfma_f32_16x16x32_bf16 v[80:83], v[206:209], v[190:193], v[80:83]
	v_mfma_f32_16x16x32_bf16 v[72:75], v[214:217], v[190:193], v[72:75]
	v_mfma_f32_16x16x32_bf16 v[68:71], v[206:209], v[198:201], v[68:71]
	v_mfma_f32_16x16x32_bf16 v[64:67], v[214:217], v[198:201], v[64:67]
	s_barrier
; #define PG8_STAGE(bufoff, gbase, voff) do { _Pragma("unroll") for (int _i = 0; _i < 2; ++_i) \
;         __builtin_amdgcn_global_load_lds((const unsigned*)((const char*)(gbase) + (voff)[_i]), (LAS unsigned*)(lds + (bufoff) + ldsw + _i * 8192), 16, 0, 0); } while (0)
; #define PG8_LDA(dst, b, h) do { _Pragma("unroll") for (int m = 0; m < 4; ++m) _Pragma("unroll") for (int k = 0; k < 2; ++k) dst[m][k] = *(const LAS bf16x8*)(lds + PG8_SA(b, h) + aoff + m * 2048 + k * 1024); } while (0)
; #define PG8_MMA(ai, bj, At, Bt) do { __builtin_amdgcn_s_setprio(1); _Pragma("unroll") for (int m = 0; m < 4; ++m) _Pragma("unroll") for (int n = 0; n < 2; ++n) _Pragma("unroll") for (int k = 0; k < 2; ++k) \
;         acc[ai][bj][m][n] = __builtin_amdgcn_mfma_f32_16x16x32_bf16(Bt[n][k], At[m][k], acc[ai][bj][m][n], 0, 0, 0); __builtin_amdgcn_s_setprio(0); } while (0)
; #define PG8_WAIT_V(n) asm volatile("s_waitcnt vmcnt(" #n ")" ::: "memory")
; #define PG8_WAIT_L(n) asm volatile("s_waitcnt lgkmcnt(" #n ")" ::: "memory")
; #define PG8_BAR __builtin_amdgcn_s_barrier()
; #define PG8_SCHED __builtin_amdgcn_sched_barrier(0)
; template <class Epi>
; __device__ __forceinline__ void gemm_phase(LAS unsigned char* lds, const Gemm g, const StaticOrder& S, const Epi& E) {
;     ...
;         for (int t = 0; t < nt; t += 2) {
;     ...
;             PG8_LDA(At, 1, 1); PG8_STAGE(PG8_SA(1, 0), a3, voffA);
;             PG8_BAR; PG8_WAIT_L(0); PG8_MMA(1, 0, At, B0); PG8_BAR; PG8_SCHED;
;             PG8_STAGE(PG8_SB(1, 1), b3 + hstepB, voffB);
;             PG8_WAIT_V(6); PG8_BAR; PG8_MMA(1, 1, At, B1); PG8_BAR;
	ds_read_b128 v[170:173], v159 offset:49152
	ds_read_b128 v[174:177], v159 offset:50176
	ds_read_b128 v[178:181], v159 offset:51200
	ds_read_b128 v[182:185], v159 offset:52224
	ds_read_b128 v[186:189], v159 offset:53248
	ds_read_b128 v[190:193], v159 offset:54272
	ds_read_b128 v[194:197], v159 offset:55296
	ds_read_b128 v[198:201], v159 offset:56320
	s_add_i32 s59, s59, s33
	s_mov_b32 m0, s59
	v_lshl_add_u64 v[152:153], v[152:153], 0, s[12:13]
	global_load_lds_dwordx4 v[152:153], off
	s_add_i32 m0, s59, 0x2000
	v_lshl_add_u64 v[152:153], v[218:219], 0, s[12:13]
	global_load_lds_dwordx4 v[152:153], off
	s_mov_b32 m0, s73
	v_lshl_add_u64 v[152:153], v[220:221], 0, s[12:13]
	global_load_lds_dwordx4 v[152:153], off
	s_mov_b32 m0, s74
	v_lshl_add_u64 v[152:153], v[222:223], 0, s[12:13]
	global_load_lds_dwordx4 v[152:153], off
	s_add_u32 s66, s66, 0x40080
	s_addc_u32 s67, s67, 0
	s_add_i32 s59, s98, s33
	s_mov_b32 m0, s59
	v_lshl_add_u64 v[240:241], s[66:67], 0, v[132:133]
	global_load_lds_dwordx4 v[240:241], off
	s_add_i32 m0, s59, 0x2000
	v_lshl_add_u64 v[240:241], s[66:67], 0, v[136:137]
	global_load_lds_dwordx4 v[240:241], off
	s_waitcnt vmcnt(8) lgkmcnt(0)
	s_barrier
	v_mfma_f32_16x16x32_bf16 v[60:63], v[144:147], v[170:173], v[60:63]
	v_mfma_f32_16x16x32_bf16 v[56:59], v[162:165], v[170:173], v[56:59]
	v_mfma_f32_16x16x32_bf16 v[52:55], v[144:147], v[178:181], v[52:55]
	v_mfma_f32_16x16x32_bf16 v[44:47], v[162:165], v[178:181], v[44:47]
	v_mfma_f32_16x16x32_bf16 v[36:39], v[144:147], v[186:189], v[36:39]
	v_mfma_f32_16x16x32_bf16 v[28:31], v[162:165], v[186:189], v[28:31]
	v_mfma_f32_16x16x32_bf16 v[20:23], v[144:147], v[194:197], v[20:23]
	v_mfma_f32_16x16x32_bf16 v[12:15], v[162:165], v[194:197], v[12:15]
	v_mfma_f32_16x16x32_bf16 v[60:63], v[148:151], v[174:177], v[60:63]
	v_mfma_f32_16x16x32_bf16 v[56:59], v[166:169], v[174:177], v[56:59]
	v_mfma_f32_16x16x32_bf16 v[52:55], v[148:151], v[182:185], v[52:55]
	v_mfma_f32_16x16x32_bf16 v[44:47], v[166:169], v[182:185], v[44:47]
	v_mfma_f32_16x16x32_bf16 v[36:39], v[148:151], v[190:193], v[36:39]
	v_mfma_f32_16x16x32_bf16 v[28:31], v[166:169], v[190:193], v[28:31]
	v_mfma_f32_16x16x32_bf16 v[20:23], v[148:151], v[198:201], v[20:23]
	v_mfma_f32_16x16x32_bf16 v[12:15], v[166:169], v[198:201], v[12:15]
	v_mfma_f32_16x16x32_bf16 v[48:51], v[202:205], v[170:173], v[48:51]
	v_mfma_f32_16x16x32_bf16 v[40:43], v[210:213], v[170:173], v[40:43]
	v_mfma_f32_16x16x32_bf16 v[32:35], v[202:205], v[178:181], v[32:35]
	v_mfma_f32_16x16x32_bf16 v[24:27], v[210:213], v[178:181], v[24:27]
	v_mfma_f32_16x16x32_bf16 v[16:19], v[202:205], v[186:189], v[16:19]
	v_mfma_f32_16x16x32_bf16 v[8:11], v[210:213], v[186:189], v[8:11]
	v_mfma_f32_16x16x32_bf16 v[4:7], v[202:205], v[194:197], v[4:7]
	v_mfma_f32_16x16x32_bf16 v[0:3], v[210:213], v[194:197], v[0:3]
	v_mfma_f32_16x16x32_bf16 v[48:51], v[206:209], v[174:177], v[48:51]
	v_mfma_f32_16x16x32_bf16 v[40:43], v[214:217], v[174:177], v[40:43]
	v_mfma_f32_16x16x32_bf16 v[32:35], v[206:209], v[182:185], v[32:35]
	v_mfma_f32_16x16x32_bf16 v[24:27], v[214:217], v[182:185], v[24:27]
	v_mfma_f32_16x16x32_bf16 v[16:19], v[206:209], v[190:193], v[16:19]
	v_mfma_f32_16x16x32_bf16 v[8:11], v[214:217], v[190:193], v[8:11]
	v_mfma_f32_16x16x32_bf16 v[4:7], v[206:209], v[198:201], v[4:7]
	v_mfma_f32_16x16x32_bf16 v[0:3], v[214:217], v[198:201], v[0:3]
	s_add_u32 s64, s64, 0x100
	s_addc_u32 s65, s65, 0
	s_add_u32 s31, s31, 0x100
	s_addc_u32 s57, s57, 0
	s_cmp_ge_i32 s85, s84
	s_mov_b32 s59, s85
	s_barrier
	s_cbranch_scc0 .LBB0_456
;     __device__ __forceinline__ void operator()(const f32x4 (&acc)[2][2][4][2], const Unit& u, int wr, int wc, int fr, int fq) const {
;     ...
;         if (u.part) {
;             float* base = tailacc + (size_t)(u.part - 1) * slab - (size_t)tail_row0 * tail_ld;
; #pragma unroll
;             for (int ai = 0; ai < 2; ++ai)
; #pragma unroll
;                 for (int m = 0; m < 4; ++m) { float* rowp = base + (size_t)(row0 + ai * HALF + m * 16) * tail_ld + col0;
; #pragma unroll
;                     for (int bj = 0; bj < 2; ++bj)
; #pragma unroll
;                         for (int n = 0; n < 2; ++n) *(f32x4*)(rowp + bj * HALF + 4 * n) = acc[ai][bj][m][n]; }
;             return;
	v_lshl_add_u32 v152, s8, 8, v155
	v_lshl_or_b32 v144, s30, 8, v157
	v_or_b32_e32 v150, 16, v152
	v_or_b32_e32 v148, 32, v152
	v_or_b32_e32 v146, 48, v152
	s_cmp_lg_u32 s81, 0
	v_ashrrev_i32_e32 v145, 31, v144
	v_ashrrev_i32_e32 v153, 31, v152
	v_ashrrev_i32_e32 v151, 31, v150
	v_ashrrev_i32_e32 v149, 31, v148
	v_ashrrev_i32_e32 v147, 31, v146
	s_cbranch_scc0 .LBB0_459
	s_add_i32 s8, s81, -1
	s_lshl_b64 s[30:31], s[8:9], 21
	s_add_u32 s30, s4, s30
	s_addc_u32 s31, s5, s31
	v_lshl_add_u64 v[162:163], v[144:145], 2, s[30:31]
	s_brev_b32 s30, 63
	s_mov_b32 s31, -1
	v_lshl_add_u64 v[162:163], v[162:163], 0, s[30:31]
	v_lshlrev_b64 v[164:165], 12, v[152:153]
	v_lshlrev_b64 v[166:167], 12, v[150:151]
	v_lshl_add_u64 v[164:165], v[162:163], 0, v[164:165]
	v_lshl_add_u64 v[166:167], v[162:163], 0, v[166:167]
	global_store_dwordx4 v[164:165], v[124:127], off
	global_store_dwordx4 v[164:165], v[120:123], off offset:16
	global_store_dwordx4 v[164:165], v[112:115], off offset:512
	global_store_dwordx4 v[164:165], v[104:107], off offset:528
	global_store_dwordx4 v[166:167], v[116:119], off
	global_store_dwordx4 v[166:167], v[108:111], off offset:16
	global_store_dwordx4 v[166:167], v[96:99], off offset:512
	global_store_dwordx4 v[166:167], v[88:91], off offset:528
	v_lshlrev_b64 v[166:167], 12, v[148:149]
	v_lshl_add_u64 v[166:167], v[162:163], 0, v[166:167]
	global_store_dwordx4 v[166:167], v[100:103], off
	global_store_dwordx4 v[166:167], v[92:95], off offset:16
	global_store_dwordx4 v[166:167], v[80:83], off offset:512
	global_store_dwordx4 v[166:167], v[72:75], off offset:528
	v_lshlrev_b64 v[166:167], 12, v[146:147]
	s_mov_b32 s8, 0x80000
	v_lshl_add_u64 v[162:163], v[162:163], 0, v[166:167]
	v_add_co_u32_e32 v166, vcc, s8, v164
	s_mov_b64 s[30:31], 0x80000
	s_nop 0
	v_addc_co_u32_e32 v167, vcc, 0, v165, vcc
	s_mov_b32 s8, 0x90000
	global_store_dwordx4 v[162:163], v[84:87], off
	global_store_dwordx4 v[162:163], v[76:79], off offset:16
	global_store_dwordx4 v[162:163], v[68:71], off offset:512
	global_store_dwordx4 v[162:163], v[64:67], off offset:528
	v_lshl_add_u64 v[162:163], v[164:165], 0, s[30:31]
	global_store_dwordx4 v[166:167], v[60:63], off
	global_store_dwordx4 v[162:163], v[56:59], off offset:16
	global_store_dwordx4 v[162:163], v[48:51], off offset:512
	global_store_dwordx4 v[162:163], v[40:43], off offset:528
	v_add_co_u32_e32 v166, vcc, s8, v164
	s_mov_b64 s[30:31], 0x90000
	s_nop 0
	v_addc_co_u32_e32 v167, vcc, 0, v165, vcc
	s_mov_b32 s8, 0xa0000
	v_lshl_add_u64 v[162:163], v[164:165], 0, s[30:31]
	global_store_dwordx4 v[166:167], v[52:55], off
	global_store_dwordx4 v[162:163], v[44:47], off offset:16
	global_store_dwordx4 v[162:163], v[32:35], off offset:512
	global_store_dwordx4 v[162:163], v[24:27], off offset:528
	s_mov_b64 s[30:31], 0xa0000
	v_add_co_u32_e32 v166, vcc, s8, v164
	v_lshl_add_u64 v[162:163], v[164:165], 0, s[30:31]
	s_nop 0
	v_addc_co_u32_e32 v167, vcc, 0, v165, vcc
	s_mov_b64 s[30:31], 0xb0000
	global_store_dwordx4 v[166:167], v[36:39], off
	global_store_dwordx4 v[162:163], v[28:31], off offset:16
	global_store_dwordx4 v[162:163], v[16:19], off offset:512
	global_store_dwordx4 v[162:163], v[8:11], off offset:528
	v_lshl_add_u64 v[162:163], v[164:165], 0, s[30:31]
	v_add_co_u32_e32 v164, vcc, 0xb0000, v164
	s_nop 1
	v_addc_co_u32_e32 v165, vcc, 0, v165, vcc
	global_store_dwordx4 v[164:165], v[20:23], off
	global_store_dwordx4 v[162:163], v[12:15], off offset:16
	global_store_dwordx4 v[162:163], v[4:7], off offset:512
	global_store_dwordx4 v[162:163], v[0:3], off offset:528
	s_cbranch_execnz .LBB0_441
	s_branch .LBB0_440

; #define PG8_STAGE(bufoff, gbase, voff) do { _Pragma("unroll") for (int _i = 0; _i < 2; ++_i) \
;         __builtin_amdgcn_global_load_lds((const unsigned*)((const char*)(gbase) + (voff)[_i]), (LAS unsigned*)(lds + (bufoff) + ldsw + _i * 8192), 16, 0, 0); } while (0)
; #define PG8_LDA(dst, b, h) do { _Pragma("unroll") for (int m = 0; m < 4; ++m) _Pragma("unroll") for (int k = 0; k < 2; ++k) dst[m][k] = *(const LAS bf16x8*)(lds + PG8_SA(b, h) + aoff + m * 2048 + k * 1024); } while (0)
; #define PG8_LDB(dst, b, h) do { _Pragma("unroll") for (int n = 0; n < 2; ++n) _Pragma("unroll") for (int k = 0; k < 2; ++k) dst[n][k] = *(const LAS bf16x8*)(lds + PG8_SB(b, h) + boff + n * 2048 + k * 1024); } while (0)
; #define PG8_WAIT_V(n) asm volatile("s_waitcnt vmcnt(" #n ")" ::: "memory")
; #define PG8_WAIT_L(n) asm volatile("s_waitcnt lgkmcnt(" #n ")" ::: "memory")
; #define PG8_BAR __builtin_amdgcn_s_barrier()
; #define PG8_SCHED __builtin_amdgcn_sched_barrier(0)
; template <class Epi>
; __device__ __forceinline__ void gemm_phase(LAS unsigned char* lds, const Gemm g, const StaticOrder& S, const Epi& E) {
;     ...
;         const bool has_next = S.next(ui + 1, nxt);
;         const char* nA = has_next ? (const char*)g.A + (size_t)nxt.pm * tstepA + (size_t)nxt.kt0 * kstep : cA; const char* nB = has_next ? (const char*)g.Bt + (size_t)nxt.pn * tstepB + (size_t)nxt.kt0 * kstep : cB;
;         const int nt = cur.nkt;
;         for (int t = 0; t < nt; t += 2) {
;             const bool last = (t == nt - 2);
;             const char* a1 = cA + (size_t)(t + 1) * kstep;
;             const char* a2 = last ? nA : cA + (size_t)(t + 2) * kstep; const char* b2 = last ? nB : cB + (size_t)(t + 2) * kstep;
;             const char* a3 = a2 + kstep; const char* b3 = b2 + kstep;
;             PG8_LDB(B0, 0, 0); PG8_SCHED; PG8_LDA(At, 0, 0); PG8_STAGE(PG8_SA(1, 1), a1 + hstepA, voffA);
;             PG8_WAIT_L(8); PG8_BAR; PG8_WAIT_L(0); PG8_MMA(0, 0, At, B0); PG8_BAR; PG8_SCHED;
;             PG8_LDB(B1, 0, 1); PG8_STAGE(PG8_SB(0, 0), b2, voffB);
;             PG8_BAR; PG8_WAIT_L(0); PG8_MMA(0, 1, At, B1); PG8_BAR;
;             PG8_LDA(At, 0, 1); PG8_STAGE(PG8_SA(0, 0), a2, voffA);
;             PG8_BAR; PG8_WAIT_L(0); PG8_MMA(1, 0, At, B0); PG8_BAR; PG8_SCHED;
;             PG8_STAGE(PG8_SB(0, 1), b2 + hstepB, voffB);
;             PG8_WAIT_V(6); PG8_BAR; PG8_MMA(1, 1, At, B1); PG8_BAR;
.LBB0_682:
	s_add_u32 s62, s60, 0xfffc0080
	s_addc_u32 s63, s61, -1
	s_cmp_eq_u32 s78, 12
	s_cselect_b32 s65, s41, s63
	s_cselect_b32 s64, s40, s62
	s_cselect_b32 s63, s57, s39
	s_cselect_b32 s62, s56, s37
	ds_read_b128 v[152:155], v159
	ds_read_b128 v[162:165], v159 offset:1024
	ds_read_b128 v[166:169], v159 offset:2048
	ds_read_b128 v[170:173], v159 offset:3072
	ds_read_b128 v[174:177], v160
	ds_read_b128 v[178:181], v160 offset:1024
	ds_read_b128 v[182:185], v160 offset:2048
	ds_read_b128 v[186:189], v160 offset:3072
	ds_read_b128 v[190:193], v160 offset:4096
	ds_read_b128 v[194:197], v160 offset:5120
	ds_read_b128 v[198:201], v160 offset:6144
	ds_read_b128 v[202:205], v160 offset:7168
	ds_read_b128 v[206:209], v161
	ds_read_b128 v[210:213], v161 offset:1024
	ds_read_b128 v[214:217], v161 offset:2048
	ds_read_b128 v[218:221], v161 offset:3072
	s_add_i32 m0, s35, 0xc000
	v_lshl_add_u64 v[242:243], s[60:61], 0, v[144:145]
	global_load_lds_dwordx4 v[242:243], off
	s_add_i32 m0, s35, 0xe000
	v_lshl_add_u64 v[242:243], s[60:61], 0, v[146:147]
	global_load_lds_dwordx4 v[242:243], off
	s_waitcnt vmcnt(8) lgkmcnt(0)
	s_barrier
	v_mfma_f32_16x16x32_bf16 v[124:127], v[152:155], v[174:177], v[124:127]
	v_mfma_f32_16x16x32_bf16 v[120:123], v[166:169], v[174:177], v[120:123]
	v_mfma_f32_16x16x32_bf16 v[116:119], v[152:155], v[182:185], v[116:119]
	v_mfma_f32_16x16x32_bf16 v[108:111], v[166:169], v[182:185], v[108:111]
	v_mfma_f32_16x16x32_bf16 v[100:103], v[152:155], v[190:193], v[100:103]
	v_mfma_f32_16x16x32_bf16 v[92:95], v[166:169], v[190:193], v[92:95]
	v_mfma_f32_16x16x32_bf16 v[84:87], v[152:155], v[198:201], v[84:87]
	v_mfma_f32_16x16x32_bf16 v[76:79], v[166:169], v[198:201], v[76:79]
	v_mfma_f32_16x16x32_bf16 v[124:127], v[162:165], v[178:181], v[124:127]
	v_mfma_f32_16x16x32_bf16 v[120:123], v[170:173], v[178:181], v[120:123]
	v_mfma_f32_16x16x32_bf16 v[116:119], v[162:165], v[186:189], v[116:119]
	v_mfma_f32_16x16x32_bf16 v[108:111], v[170:173], v[186:189], v[108:111]
	v_mfma_f32_16x16x32_bf16 v[100:103], v[162:165], v[194:197], v[100:103]
	v_mfma_f32_16x16x32_bf16 v[92:95], v[170:173], v[194:197], v[92:95]
	v_mfma_f32_16x16x32_bf16 v[84:87], v[162:165], v[202:205], v[84:87]
	v_mfma_f32_16x16x32_bf16 v[76:79], v[170:173], v[202:205], v[76:79]
	v_mfma_f32_16x16x32_bf16 v[112:115], v[206:209], v[174:177], v[112:115]
	v_mfma_f32_16x16x32_bf16 v[104:107], v[214:217], v[174:177], v[104:107]
	v_mfma_f32_16x16x32_bf16 v[96:99], v[206:209], v[182:185], v[96:99]
	v_mfma_f32_16x16x32_bf16 v[88:91], v[214:217], v[182:185], v[88:91]
	v_mfma_f32_16x16x32_bf16 v[80:83], v[206:209], v[190:193], v[80:83]
	v_mfma_f32_16x16x32_bf16 v[72:75], v[214:217], v[190:193], v[72:75]
	v_mfma_f32_16x16x32_bf16 v[68:71], v[206:209], v[198:201], v[68:71]
	v_mfma_f32_16x16x32_bf16 v[64:67], v[214:217], v[198:201], v[64:67]
	v_mfma_f32_16x16x32_bf16 v[112:115], v[210:213], v[178:181], v[112:115]
	v_mfma_f32_16x16x32_bf16 v[104:107], v[218:221], v[178:181], v[104:107]
	v_mfma_f32_16x16x32_bf16 v[96:99], v[210:213], v[186:189], v[96:99]
	v_mfma_f32_16x16x32_bf16 v[88:91], v[218:221], v[186:189], v[88:91]
	v_mfma_f32_16x16x32_bf16 v[80:83], v[210:213], v[194:197], v[80:83]
	v_mfma_f32_16x16x32_bf16 v[72:75], v[218:221], v[194:197], v[72:75]
	v_mfma_f32_16x16x32_bf16 v[68:71], v[210:213], v[202:205], v[68:71]
	v_mfma_f32_16x16x32_bf16 v[64:67], v[218:221], v[202:205], v[64:67]
	s_barrier
	ds_read_b128 v[174:177], v160 offset:16384
	ds_read_b128 v[178:181], v160 offset:17408
	ds_read_b128 v[182:185], v160 offset:18432
	ds_read_b128 v[186:189], v160 offset:19456
	ds_read_b128 v[190:193], v160 offset:20480
	ds_read_b128 v[194:197], v160 offset:21504
	ds_read_b128 v[198:201], v160 offset:22528
	ds_read_b128 v[202:205], v160 offset:23552
	s_add_i32 s79, s75, s33
	s_mov_b32 m0, s79
	v_lshl_add_u64 v[222:223], s[62:63], 0, v[138:139]
	global_load_lds_dwordx4 v[222:223], off
	s_add_i32 m0, s79, 0x2000
	v_lshl_add_u64 v[224:225], s[62:63], 0, v[142:143]
	global_load_lds_dwordx4 v[224:225], off
	s_mov_b32 m0, s35
	v_lshl_add_u64 v[226:227], s[64:65], 0, v[136:137]
	global_load_lds_dwordx4 v[226:227], off
	s_mov_b32 m0, s66
	v_lshl_add_u64 v[228:229], s[64:65], 0, v[140:141]
	global_load_lds_dwordx4 v[228:229], off
	s_add_u32 s80, s62, 0x40000
	s_addc_u32 s81, s63, 0
	s_add_i32 s79, s76, s33
	s_mov_b32 m0, s79
	v_lshl_add_u64 v[240:241], s[80:81], 0, v[138:139]
	global_load_lds_dwordx4 v[240:241], off
	s_add_i32 m0, s79, 0x2000
	v_lshl_add_u64 v[240:241], s[80:81], 0, v[142:143]
	global_load_lds_dwordx4 v[240:241], off
	s_waitcnt vmcnt(8) lgkmcnt(0)
	s_barrier
; #define PG8_STAGE(bufoff, gbase, voff) do { _Pragma("unroll") for (int _i = 0; _i < 2; ++_i) \
;         __builtin_amdgcn_global_load_lds((const unsigned*)((const char*)(gbase) + (voff)[_i]), (LAS unsigned*)(lds + (bufoff) + ldsw + _i * 8192), 16, 0, 0); } while (0)
; #define PG8_LDA(dst, b, h) do { _Pragma("unroll") for (int m = 0; m < 4; ++m) _Pragma("unroll") for (int k = 0; k < 2; ++k) dst[m][k] = *(const LAS bf16x8*)(lds + PG8_SA(b, h) + aoff + m * 2048 + k * 1024); } while (0)
; #define PG8_LDB(dst, b, h) do { _Pragma("unroll") for (int n = 0; n < 2; ++n) _Pragma("unroll") for (int k = 0; k < 2; ++k) dst[n][k] = *(const LAS bf16x8*)(lds + PG8_SB(b, h) + boff + n * 2048 + k * 1024); } while (0)
; #define PG8_MMA(ai, bj, At, Bt) do { __builtin_amdgcn_s_setprio(1); _Pragma("unroll") for (int m = 0; m < 4; ++m) _Pragma("unroll") for (int n = 0; n < 2; ++n) _Pragma("unroll") for (int k = 0; k < 2; ++k) \
;         acc[ai][bj][m][n] = __builtin_amdgcn_mfma_f32_16x16x32_bf16(Bt[n][k], At[m][k], acc[ai][bj][m][n], 0, 0, 0); __builtin_amdgcn_s_setprio(0); } while (0)
; #define PG8_WAIT_V(n) asm volatile("s_waitcnt vmcnt(" #n ")" ::: "memory")
; #define PG8_WAIT_L(n) asm volatile("s_waitcnt lgkmcnt(" #n ")" ::: "memory")
; #define PG8_BAR __builtin_amdgcn_s_barrier()
; #define PG8_SCHED __builtin_amdgcn_sched_barrier(0)
; template <class Epi>
; __device__ __forceinline__ void gemm_phase(LAS unsigned char* lds, const Gemm g, const StaticOrder& S, const Epi& E) {
;     ...
;             PG8_BAR; PG8_WAIT_L(0); PG8_MMA(1, 0, At, B0); PG8_BAR; PG8_SCHED;
;             PG8_STAGE(PG8_SB(0, 1), b2 + hstepB, voffB);
;             PG8_WAIT_V(6); PG8_BAR; PG8_MMA(1, 1, At, B1); PG8_BAR;
;             PG8_LDB(B0, 1, 0); PG8_SCHED; PG8_LDA(At, 1, 0); PG8_STAGE(PG8_SA(0, 1), a2 + hstepA, voffA);
;             PG8_WAIT_L(8); PG8_BAR; PG8_WAIT_L(0); PG8_MMA(0, 0, At, B0); PG8_BAR; PG8_SCHED;
;             PG8_LDB(B1, 1, 1); PG8_STAGE(PG8_SB(1, 0), b3, voffB);
;             PG8_BAR; PG8_WAIT_L(0); PG8_MMA(0, 1, At, B1); PG8_BAR;
	v_mfma_f32_16x16x32_bf16 v[60:63], v[152:155], v[174:177], v[60:63]
	v_mfma_f32_16x16x32_bf16 v[56:59], v[166:169], v[174:177], v[56:59]
	v_mfma_f32_16x16x32_bf16 v[52:55], v[152:155], v[182:185], v[52:55]
	v_mfma_f32_16x16x32_bf16 v[44:47], v[166:169], v[182:185], v[44:47]
	v_mfma_f32_16x16x32_bf16 v[36:39], v[152:155], v[190:193], v[36:39]
	v_mfma_f32_16x16x32_bf16 v[28:31], v[166:169], v[190:193], v[28:31]
	v_mfma_f32_16x16x32_bf16 v[20:23], v[152:155], v[198:201], v[20:23]
	v_mfma_f32_16x16x32_bf16 v[12:15], v[166:169], v[198:201], v[12:15]
	v_mfma_f32_16x16x32_bf16 v[60:63], v[162:165], v[178:181], v[60:63]
	v_mfma_f32_16x16x32_bf16 v[56:59], v[170:173], v[178:181], v[56:59]
	v_mfma_f32_16x16x32_bf16 v[52:55], v[162:165], v[186:189], v[52:55]
	v_mfma_f32_16x16x32_bf16 v[44:47], v[170:173], v[186:189], v[44:47]
	v_mfma_f32_16x16x32_bf16 v[36:39], v[162:165], v[194:197], v[36:39]
	v_mfma_f32_16x16x32_bf16 v[28:31], v[170:173], v[194:197], v[28:31]
	v_mfma_f32_16x16x32_bf16 v[20:23], v[162:165], v[202:205], v[20:23]
	v_mfma_f32_16x16x32_bf16 v[12:15], v[170:173], v[202:205], v[12:15]
	v_mfma_f32_16x16x32_bf16 v[48:51], v[206:209], v[174:177], v[48:51]
	v_mfma_f32_16x16x32_bf16 v[40:43], v[214:217], v[174:177], v[40:43]
	v_mfma_f32_16x16x32_bf16 v[32:35], v[206:209], v[182:185], v[32:35]
	v_mfma_f32_16x16x32_bf16 v[24:27], v[214:217], v[182:185], v[24:27]
	v_mfma_f32_16x16x32_bf16 v[16:19], v[206:209], v[190:193], v[16:19]
	v_mfma_f32_16x16x32_bf16 v[8:11], v[214:217], v[190:193], v[8:11]
	v_mfma_f32_16x16x32_bf16 v[4:7], v[206:209], v[198:201], v[4:7]
	v_mfma_f32_16x16x32_bf16 v[0:3], v[214:217], v[198:201], v[0:3]
	v_mfma_f32_16x16x32_bf16 v[48:51], v[210:213], v[178:181], v[48:51]
	v_mfma_f32_16x16x32_bf16 v[40:43], v[218:221], v[178:181], v[40:43]
	v_mfma_f32_16x16x32_bf16 v[32:35], v[210:213], v[186:189], v[32:35]
	v_mfma_f32_16x16x32_bf16 v[24:27], v[218:221], v[186:189], v[24:27]
	v_mfma_f32_16x16x32_bf16 v[16:19], v[210:213], v[194:197], v[16:19]
	v_mfma_f32_16x16x32_bf16 v[8:11], v[218:221], v[194:197], v[8:11]
	v_mfma_f32_16x16x32_bf16 v[4:7], v[210:213], v[202:205], v[4:7]
	v_mfma_f32_16x16x32_bf16 v[0:3], v[218:221], v[202:205], v[0:3]
	s_barrier
	s_add_i32 s79, 0, 0x18000
	v_add_u32_e32 v170, s79, v156
	ds_read_b128 v[152:155], v170
	ds_read_b128 v[162:165], v170 offset:1024
	ds_read_b128 v[166:169], v170 offset:2048
	ds_read_b128 v[170:173], v170 offset:3072
	ds_read_b128 v[174:177], v160 offset:32768
	ds_read_b128 v[178:181], v160 offset:33792
	ds_read_b128 v[182:185], v160 offset:34816
	ds_read_b128 v[186:189], v160 offset:35840
	ds_read_b128 v[190:193], v160 offset:36864
	ds_read_b128 v[194:197], v160 offset:37888
	ds_read_b128 v[198:201], v160 offset:38912
	ds_read_b128 v[202:205], v160 offset:39936
	s_add_i32 s98, 0, 0x1c000
	v_add_u32_e32 v218, s98, v156
	ds_read_b128 v[206:209], v218
	ds_read_b128 v[210:213], v218 offset:1024
	ds_read_b128 v[214:217], v218 offset:2048
	ds_read_b128 v[218:221], v218 offset:3072
	s_add_u32 s64, s64, 0x40000
	s_addc_u32 s65, s65, 0
	s_mov_b32 m0, s67
	v_lshl_add_u64 v[244:245], s[64:65], 0, v[136:137]
	global_load_lds_dwordx4 v[244:245], off
	s_mov_b32 m0, s68
	v_lshl_add_u64 v[244:245], s[64:65], 0, v[140:141]
	global_load_lds_dwordx4 v[244:245], off
	s_waitcnt vmcnt(8) lgkmcnt(0)
	s_barrier
	v_mfma_f32_16x16x32_bf16 v[124:127], v[152:155], v[174:177], v[124:127]
	v_mfma_f32_16x16x32_bf16 v[120:123], v[166:169], v[174:177], v[120:123]
	v_mfma_f32_16x16x32_bf16 v[116:119], v[152:155], v[182:185], v[116:119]
	v_mfma_f32_16x16x32_bf16 v[108:111], v[166:169], v[182:185], v[108:111]
	v_mfma_f32_16x16x32_bf16 v[100:103], v[152:155], v[190:193], v[100:103]
	v_mfma_f32_16x16x32_bf16 v[92:95], v[166:169], v[190:193], v[92:95]
	v_mfma_f32_16x16x32_bf16 v[84:87], v[152:155], v[198:201], v[84:87]
	v_mfma_f32_16x16x32_bf16 v[76:79], v[166:169], v[198:201], v[76:79]
	v_mfma_f32_16x16x32_bf16 v[124:127], v[162:165], v[178:181], v[124:127]
	v_mfma_f32_16x16x32_bf16 v[120:123], v[170:173], v[178:181], v[120:123]
	v_mfma_f32_16x16x32_bf16 v[116:119], v[162:165], v[186:189], v[116:119]
	v_mfma_f32_16x16x32_bf16 v[108:111], v[170:173], v[186:189], v[108:111]
	v_mfma_f32_16x16x32_bf16 v[100:103], v[162:165], v[194:197], v[100:103]
	v_mfma_f32_16x16x32_bf16 v[92:95], v[170:173], v[194:197], v[92:95]
	v_mfma_f32_16x16x32_bf16 v[84:87], v[162:165], v[202:205], v[84:87]
	v_mfma_f32_16x16x32_bf16 v[76:79], v[170:173], v[202:205], v[76:79]
	v_mfma_f32_16x16x32_bf16 v[112:115], v[206:209], v[174:177], v[112:115]
	v_mfma_f32_16x16x32_bf16 v[104:107], v[214:217], v[174:177], v[104:107]
	v_mfma_f32_16x16x32_bf16 v[96:99], v[206:209], v[182:185], v[96:99]
	v_mfma_f32_16x16x32_bf16 v[88:91], v[214:217], v[182:185], v[88:91]
	v_mfma_f32_16x16x32_bf16 v[80:83], v[206:209], v[190:193], v[80:83]
	v_mfma_f32_16x16x32_bf16 v[72:75], v[214:217], v[190:193], v[72:75]
	v_mfma_f32_16x16x32_bf16 v[68:71], v[206:209], v[198:201], v[68:71]
	v_mfma_f32_16x16x32_bf16 v[64:67], v[214:217], v[198:201], v[64:67]
	v_mfma_f32_16x16x32_bf16 v[112:115], v[210:213], v[178:181], v[112:115]
	v_mfma_f32_16x16x32_bf16 v[104:107], v[218:221], v[178:181], v[104:107]
	v_mfma_f32_16x16x32_bf16 v[96:99], v[210:213], v[186:189], v[96:99]
	v_mfma_f32_16x16x32_bf16 v[88:91], v[218:221], v[186:189], v[88:91]
	v_mfma_f32_16x16x32_bf16 v[80:83], v[210:213], v[194:197], v[80:83]
	v_mfma_f32_16x16x32_bf16 v[72:75], v[218:221], v[194:197], v[72:75]
	v_mfma_f32_16x16x32_bf16 v[68:71], v[210:213], v[202:205], v[68:71]
	v_mfma_f32_16x16x32_bf16 v[64:67], v[218:221], v[202:205], v[64:67]
	s_barrier
; __device__ __forceinline__ unsigned pk2(float lo, float hi) { unsigned r; asm("v_cvt_pk_bf16_f32 %0, %1, %2" : "=v"(r) : "v"(lo), "v"(hi)); return r; }
; __device__ __forceinline__ float gelu_t(float x) { return x * __builtin_amdgcn_rcpf(1.f + __expf(-1.5957691216057308f * (x + 0.044715f * x * x * x))); }
; #define PG8_STAGE(bufoff, gbase, voff) do { _Pragma("unroll") for (int _i = 0; _i < 2; ++_i) \
;         __builtin_amdgcn_global_load_lds((const unsigned*)((const char*)(gbase) + (voff)[_i]), (LAS unsigned*)(lds + (bufoff) + ldsw + _i * 8192), 16, 0, 0); } while (0)
; #define PG8_LDA(dst, b, h) do { _Pragma("unroll") for (int m = 0; m < 4; ++m) _Pragma("unroll") for (int k = 0; k < 2; ++k) dst[m][k] = *(const LAS bf16x8*)(lds + PG8_SA(b, h) + aoff + m * 2048 + k * 1024); } while (0)
; #define PG8_WAIT_V(n) asm volatile("s_waitcnt vmcnt(" #n ")" ::: "memory")
; #define PG8_WAIT_L(n) asm volatile("s_waitcnt lgkmcnt(" #n ")" ::: "memory")
;     __device__ __forceinline__ void operator()(const f32x4 (&acc)[2][2][4][2], const Unit& u, int wr, int wc, int fr, int fq) const {
;     ...
; #pragma unroll
;         for (int ai = 0; ai < 2; ++ai)
; #pragma unroll
;             for (int m = 0; m < 4; ++m) { const int row = row0 + ai * HALF + m * 16; u16* rowp = O + (size_t)row * ldc + col0;
; #pragma unroll
;                 for (int bj = 0; bj < 2; ++bj) { f32x4 v0 = acc[ai][bj][m][0], v1 = acc[ai][bj][m][1];
;                     if (col0 + bj * HALF >= gelu_from) { v0 = (f32x4){gelu_t(v0.x), gelu_t(v0.y), gelu_t(v0.z), gelu_t(v0.w)}; v1 = (f32x4){gelu_t(v1.x), gelu_t(v1.y), gelu_t(v1.z), gelu_t(v1.w)}; }
;                     u32x4 w; w.x = pk2(v0[0], v0[1]); w.y = pk2(v0[2], v0[3]); w.z = pk2(v1[0], v1[1]); w.w = pk2(v1[2], v1[3]);
;                     *(u32x4*)(rowp + bj * HALF) = w;
;                     if (halo != nullptr && m == 3 && fr >= 14) *(u32x4*)(halo + (size_t)((row >> 6) * 2 + (fr - 14)) * ldc + col0 + bj * HALF) = w; } }
; template <class Epi>
; __device__ __forceinline__ void gemm_phase(LAS unsigned char* lds, const Gemm g, const StaticOrder& S, const Epi& E) {
;     ...
;             PG8_LDA(At, 1, 1); PG8_STAGE(PG8_SA(1, 0), a3, voffA);
;             PG8_BAR; PG8_WAIT_L(0); PG8_MMA(1, 0, At, B0); PG8_BAR; PG8_SCHED;
;             PG8_STAGE(PG8_SB(1, 1), b3 + hstepB, voffB);
;             PG8_WAIT_V(6); PG8_BAR; PG8_MMA(1, 1, At, B1); PG8_BAR;
	ds_read_b128 v[174:177], v160 offset:49152
	ds_read_b128 v[178:181], v160 offset:50176
	ds_read_b128 v[182:185], v160 offset:51200
	ds_read_b128 v[186:189], v160 offset:52224
	ds_read_b128 v[190:193], v160 offset:53248
	ds_read_b128 v[194:197], v160 offset:54272
	ds_read_b128 v[198:201], v160 offset:55296
	ds_read_b128 v[202:205], v160 offset:56320
	s_add_i32 s65, s79, s33
	s_mov_b32 m0, s65
	v_lshl_add_u64 v[222:223], v[222:223], 0, s[28:29]
	global_load_lds_dwordx4 v[222:223], off
	s_add_i32 m0, s65, 0x2000
	v_lshl_add_u64 v[222:223], v[224:225], 0, s[28:29]
	global_load_lds_dwordx4 v[222:223], off
	s_mov_b32 m0, s71
	v_lshl_add_u64 v[222:223], v[226:227], 0, s[28:29]
	global_load_lds_dwordx4 v[222:223], off
	s_mov_b32 m0, s72
	v_lshl_add_u64 v[222:223], v[228:229], 0, s[28:29]
	global_load_lds_dwordx4 v[222:223], off
	s_add_u32 s62, s62, 0x40080
	s_addc_u32 s63, s63, 0
	s_add_i32 s64, s98, s33
	s_mov_b32 m0, s64
	v_lshl_add_u64 v[240:241], s[62:63], 0, v[138:139]
	global_load_lds_dwordx4 v[240:241], off
	s_add_i32 m0, s64, 0x2000
	v_lshl_add_u64 v[240:241], s[62:63], 0, v[142:143]
	global_load_lds_dwordx4 v[240:241], off
	s_waitcnt vmcnt(8) lgkmcnt(0)
	s_barrier
	v_mfma_f32_16x16x32_bf16 v[60:63], v[152:155], v[174:177], v[60:63]
	v_mfma_f32_16x16x32_bf16 v[56:59], v[166:169], v[174:177], v[56:59]
	v_mfma_f32_16x16x32_bf16 v[52:55], v[152:155], v[182:185], v[52:55]
	v_mfma_f32_16x16x32_bf16 v[44:47], v[166:169], v[182:185], v[44:47]
	v_mfma_f32_16x16x32_bf16 v[36:39], v[152:155], v[190:193], v[36:39]
	v_mfma_f32_16x16x32_bf16 v[28:31], v[166:169], v[190:193], v[28:31]
	v_mfma_f32_16x16x32_bf16 v[20:23], v[152:155], v[198:201], v[20:23]
	v_mfma_f32_16x16x32_bf16 v[12:15], v[166:169], v[198:201], v[12:15]
	v_mfma_f32_16x16x32_bf16 v[60:63], v[162:165], v[178:181], v[60:63]
	v_mfma_f32_16x16x32_bf16 v[56:59], v[170:173], v[178:181], v[56:59]
	v_mfma_f32_16x16x32_bf16 v[52:55], v[162:165], v[186:189], v[52:55]
	v_mfma_f32_16x16x32_bf16 v[44:47], v[170:173], v[186:189], v[44:47]
	v_mfma_f32_16x16x32_bf16 v[36:39], v[162:165], v[194:197], v[36:39]
	v_mfma_f32_16x16x32_bf16 v[28:31], v[170:173], v[194:197], v[28:31]
	v_mfma_f32_16x16x32_bf16 v[20:23], v[162:165], v[202:205], v[20:23]
	v_mfma_f32_16x16x32_bf16 v[12:15], v[170:173], v[202:205], v[12:15]
	v_mfma_f32_16x16x32_bf16 v[48:51], v[206:209], v[174:177], v[48:51]
	v_mfma_f32_16x16x32_bf16 v[40:43], v[214:217], v[174:177], v[40:43]
	v_mfma_f32_16x16x32_bf16 v[32:35], v[206:209], v[182:185], v[32:35]
	v_mfma_f32_16x16x32_bf16 v[24:27], v[214:217], v[182:185], v[24:27]
	v_mfma_f32_16x16x32_bf16 v[16:19], v[206:209], v[190:193], v[16:19]
	v_mfma_f32_16x16x32_bf16 v[8:11], v[214:217], v[190:193], v[8:11]
	v_mfma_f32_16x16x32_bf16 v[4:7], v[206:209], v[198:201], v[4:7]
	v_mfma_f32_16x16x32_bf16 v[0:3], v[214:217], v[198:201], v[0:3]
	v_mfma_f32_16x16x32_bf16 v[48:51], v[210:213], v[178:181], v[48:51]
	v_mfma_f32_16x16x32_bf16 v[40:43], v[218:221], v[178:181], v[40:43]
	v_mfma_f32_16x16x32_bf16 v[32:35], v[210:213], v[186:189], v[32:35]
	v_mfma_f32_16x16x32_bf16 v[24:27], v[218:221], v[186:189], v[24:27]
	v_mfma_f32_16x16x32_bf16 v[16:19], v[210:213], v[194:197], v[16:19]
	v_mfma_f32_16x16x32_bf16 v[8:11], v[218:221], v[194:197], v[8:11]
	v_mfma_f32_16x16x32_bf16 v[4:7], v[210:213], v[202:205], v[4:7]
	v_mfma_f32_16x16x32_bf16 v[0:3], v[218:221], v[202:205], v[0:3]
	s_add_i32 s78, s78, 2
	s_add_u32 s60, s60, 0x100
	s_addc_u32 s61, s61, 0
	s_add_u32 s37, s37, 0x100
	s_addc_u32 s39, s39, 0
	s_cmp_gt_u32 s78, 13
	s_barrier
	s_cbranch_scc0 .LBB0_682
	s_lshl_b32 s37, s58, 8
	s_add_i32 s37, s37, s70
	v_lshl_or_b32 v152, s59, 8, v158
	v_or_b32_e32 v162, s37, v135
	v_ashrrev_i32_e32 v153, 31, v152
	v_mov_b64_e32 v[164:165], s[4:5]
	v_mad_i64_i32 v[166:167], s[58:59], v162, s77, v[164:165]
	v_lshlrev_b64 v[154:155], 1, v[152:153]
	v_cvt_pk_bf16_f32 v112, v112, v113
	v_cvt_pk_bf16_f32 v113, v114, v115
	v_cvt_pk_bf16_f32 v114, v104, v105
	v_or_b32_e32 v104, 16, v162
	v_lshl_add_u64 v[166:167], v[166:167], 0, v[154:155]
	v_mad_i64_i32 v[104:105], s[58:59], v104, s77, v[164:165]
	v_cvt_pk_bf16_f32 v96, v96, v97
	v_cvt_pk_bf16_f32 v97, v98, v99
	v_cvt_pk_bf16_f32 v98, v88, v89
	v_or_b32_e32 v88, 32, v162
	v_cvt_pk_bf16_f32 v115, v106, v107
	global_store_dwordx4 v[166:167], v[112:115], off offset:256
	v_mad_i64_i32 v[88:89], s[58:59], v88, s77, v[164:165]
	s_nop 0
	v_lshl_add_u64 v[112:113], v[104:105], 0, v[154:155]
	v_cvt_pk_bf16_f32 v80, v80, v81
	v_cvt_pk_bf16_f32 v81, v82, v83
	v_cvt_pk_bf16_f32 v82, v72, v73
	v_or_b32_e32 v72, 48, v162
	s_ashr_i32 s37, s37, 5
	v_cvt_pk_bf16_f32 v99, v90, v91
	global_store_dwordx4 v[112:113], v[96:99], off offset:256
	v_mad_i64_i32 v[72:73], s[58:59], v72, s77, v[164:165]
	s_nop 0
	v_lshl_add_u64 v[96:97], v[88:89], 0, v[154:155]
	v_add_u32_e32 v163, s37, v157
	v_cvt_pk_bf16_f32 v83, v74, v75
	global_store_dwordx4 v[96:97], v[80:83], off offset:256
	v_cvt_pk_bf16_f32 v124, v124, v125
	v_cvt_pk_bf16_f32 v125, v126, v127
	v_cvt_pk_bf16_f32 v126, v120, v121
	v_cvt_pk_bf16_f32 v127, v122, v123
	global_store_dwordx4 v[166:167], v[124:127], off
	s_nop 0
	v_lshl_add_u64 v[80:81], v[72:73], 0, v[154:155]
	v_cvt_pk_bf16_f32 v104, v116, v117
	v_cvt_pk_bf16_f32 v105, v118, v119
	v_cvt_pk_bf16_f32 v106, v108, v109
	v_cvt_pk_bf16_f32 v107, v110, v111
	global_store_dwordx4 v[112:113], v[104:107], off
	v_cvt_pk_bf16_f32 v88, v100, v101
	v_cvt_pk_bf16_f32 v89, v102, v103
	v_cvt_pk_bf16_f32 v90, v92, v93
	v_cvt_pk_bf16_f32 v91, v94, v95
	global_store_dwordx4 v[96:97], v[88:91], off
	v_cvt_pk_bf16_f32 v72, v84, v85
	v_cvt_pk_bf16_f32 v73, v86, v87
	v_cvt_pk_bf16_f32 v74, v76, v77
	v_cvt_pk_bf16_f32 v75, v78, v79
	global_store_dwordx4 v[80:81], v[72:75], off
	s_and_saveexec_b64 s[58:59], s[0:1]
	s_cbranch_execz .LBB0_685
	v_mov_b64_e32 v[76:77], s[18:19]
	v_mad_i64_i32 v[76:77], s[60:61], v163, s77, v[76:77]
	v_lshl_add_u64 v[76:77], v[152:153], 1, v[76:77]
	global_store_dwordx4 v[76:77], v[72:75], off

; #define PG8_STAGE(bufoff, gbase, voff) do { _Pragma("unroll") for (int _i = 0; _i < 2; ++_i) \
;         __builtin_amdgcn_global_load_lds((const unsigned*)((const char*)(gbase) + (voff)[_i]), (LAS unsigned*)(lds + (bufoff) + ldsw + _i * 8192), 16, 0, 0); } while (0)
; #define PG8_LDA(dst, b, h) do { _Pragma("unroll") for (int m = 0; m < 4; ++m) _Pragma("unroll") for (int k = 0; k < 2; ++k) dst[m][k] = *(const LAS bf16x8*)(lds + PG8_SA(b, h) + aoff + m * 2048 + k * 1024); } while (0)
; #define PG8_LDB(dst, b, h) do { _Pragma("unroll") for (int n = 0; n < 2; ++n) _Pragma("unroll") for (int k = 0; k < 2; ++k) dst[n][k] = *(const LAS bf16x8*)(lds + PG8_SB(b, h) + boff + n * 2048 + k * 1024); } while (0)
; #define PG8_WAIT_V(n) asm volatile("s_waitcnt vmcnt(" #n ")" ::: "memory")
; #define PG8_WAIT_L(n) asm volatile("s_waitcnt lgkmcnt(" #n ")" ::: "memory")
; #define PG8_BAR __builtin_amdgcn_s_barrier()
; #define PG8_SCHED __builtin_amdgcn_sched_barrier(0)
; template <class Epi>
; __device__ __forceinline__ void gemm_phase(LAS unsigned char* lds, const Gemm g, const StaticOrder& S, const Epi& E) {
;     ...
;         const bool has_next = S.next(ui + 1, nxt);
;         const char* nA = has_next ? (const char*)g.A + (size_t)nxt.pm * tstepA + (size_t)nxt.kt0 * kstep : cA; const char* nB = has_next ? (const char*)g.Bt + (size_t)nxt.pn * tstepB + (size_t)nxt.kt0 * kstep : cB;
;         const int nt = cur.nkt;
;         for (int t = 0; t < nt; t += 2) {
;             const bool last = (t == nt - 2);
;             const char* a1 = cA + (size_t)(t + 1) * kstep;
;             const char* a2 = last ? nA : cA + (size_t)(t + 2) * kstep; const char* b2 = last ? nB : cB + (size_t)(t + 2) * kstep;
;             const char* a3 = a2 + kstep; const char* b3 = b2 + kstep;
;             PG8_LDB(B0, 0, 0); PG8_SCHED; PG8_LDA(At, 0, 0); PG8_STAGE(PG8_SA(1, 1), a1 + hstepA, voffA);
;             PG8_WAIT_L(8); PG8_BAR; PG8_WAIT_L(0); PG8_MMA(0, 0, At, B0); PG8_BAR; PG8_SCHED;
;             PG8_LDB(B1, 0, 1); PG8_STAGE(PG8_SB(0, 0), b2, voffB);
;             PG8_BAR; PG8_WAIT_L(0); PG8_MMA(0, 1, At, B1); PG8_BAR;
;             PG8_LDA(At, 0, 1); PG8_STAGE(PG8_SA(0, 0), a2, voffA);
;             PG8_BAR; PG8_WAIT_L(0); PG8_MMA(1, 0, At, B0); PG8_BAR; PG8_SCHED;
;             PG8_STAGE(PG8_SB(0, 1), b2 + hstepB, voffB);
;             PG8_WAIT_V(6); PG8_BAR; PG8_MMA(1, 1, At, B1); PG8_BAR;
.LBB0_910:
	s_add_i32 s83, s54, 2
	s_add_u32 s55, s46, 0xffea0080
	s_addc_u32 s56, s47, -1
	s_cmp_eq_u32 s18, s54
	s_cselect_b32 s54, s0, s41
	s_cselect_b32 s57, s45, s56
	s_cselect_b32 s56, s44, s55
	s_cselect_b32 s55, s1, s82
	ds_read_b128 v[150:153], v170
	ds_read_b128 v[154:157], v170 offset:1024
	ds_read_b128 v[174:177], v170 offset:2048
	ds_read_b128 v[178:181], v170 offset:3072
	ds_read_b128 v[182:185], v171
	ds_read_b128 v[186:189], v171 offset:1024
	ds_read_b128 v[190:193], v171 offset:2048
	ds_read_b128 v[194:197], v171 offset:3072
	ds_read_b128 v[198:201], v171 offset:4096
	ds_read_b128 v[202:205], v171 offset:5120
	ds_read_b128 v[206:209], v171 offset:6144
	ds_read_b128 v[210:213], v171 offset:7168
	ds_read_b128 v[214:217], v172
	ds_read_b128 v[218:221], v172 offset:1024
	ds_read_b128 v[222:225], v172 offset:2048
	ds_read_b128 v[226:229], v172 offset:3072
	s_add_i32 m0, s33, 0xc000
	v_lshl_add_u64 v[158:159], s[46:47], 0, v[144:145]
	global_load_lds_dwordx4 v[158:159], off
	s_add_i32 m0, s33, 0xe000
	v_lshl_add_u64 v[158:159], s[46:47], 0, v[146:147]
	global_load_lds_dwordx4 v[158:159], off
	s_waitcnt vmcnt(8) lgkmcnt(0)
	s_barrier
	v_mfma_f32_16x16x32_bf16 v[124:127], v[150:153], v[182:185], v[124:127]
	v_mfma_f32_16x16x32_bf16 v[120:123], v[174:177], v[182:185], v[120:123]
	v_mfma_f32_16x16x32_bf16 v[116:119], v[150:153], v[190:193], v[116:119]
	v_mfma_f32_16x16x32_bf16 v[108:111], v[174:177], v[190:193], v[108:111]
	v_mfma_f32_16x16x32_bf16 v[100:103], v[150:153], v[198:201], v[100:103]
	v_mfma_f32_16x16x32_bf16 v[92:95], v[174:177], v[198:201], v[92:95]
	v_mfma_f32_16x16x32_bf16 v[84:87], v[150:153], v[206:209], v[84:87]
	v_mfma_f32_16x16x32_bf16 v[76:79], v[174:177], v[206:209], v[76:79]
	v_mfma_f32_16x16x32_bf16 v[124:127], v[154:157], v[186:189], v[124:127]
	v_mfma_f32_16x16x32_bf16 v[120:123], v[178:181], v[186:189], v[120:123]
	v_mfma_f32_16x16x32_bf16 v[116:119], v[154:157], v[194:197], v[116:119]
	v_mfma_f32_16x16x32_bf16 v[108:111], v[178:181], v[194:197], v[108:111]
	v_mfma_f32_16x16x32_bf16 v[100:103], v[154:157], v[202:205], v[100:103]
	v_mfma_f32_16x16x32_bf16 v[92:95], v[178:181], v[202:205], v[92:95]
	v_mfma_f32_16x16x32_bf16 v[84:87], v[154:157], v[210:213], v[84:87]
	v_mfma_f32_16x16x32_bf16 v[76:79], v[178:181], v[210:213], v[76:79]
	v_mfma_f32_16x16x32_bf16 v[112:115], v[214:217], v[182:185], v[112:115]
	v_mfma_f32_16x16x32_bf16 v[104:107], v[222:225], v[182:185], v[104:107]
	v_mfma_f32_16x16x32_bf16 v[96:99], v[214:217], v[190:193], v[96:99]
	v_mfma_f32_16x16x32_bf16 v[88:91], v[222:225], v[190:193], v[88:91]
	v_mfma_f32_16x16x32_bf16 v[80:83], v[214:217], v[198:201], v[80:83]
	v_mfma_f32_16x16x32_bf16 v[72:75], v[222:225], v[198:201], v[72:75]
	v_mfma_f32_16x16x32_bf16 v[68:71], v[214:217], v[206:209], v[68:71]
	v_mfma_f32_16x16x32_bf16 v[64:67], v[222:225], v[206:209], v[64:67]
	v_mfma_f32_16x16x32_bf16 v[112:115], v[218:221], v[186:189], v[112:115]
	v_mfma_f32_16x16x32_bf16 v[104:107], v[226:229], v[186:189], v[104:107]
	v_mfma_f32_16x16x32_bf16 v[96:99], v[218:221], v[194:197], v[96:99]
	v_mfma_f32_16x16x32_bf16 v[88:91], v[226:229], v[194:197], v[88:91]
	v_mfma_f32_16x16x32_bf16 v[80:83], v[218:221], v[202:205], v[80:83]
	v_mfma_f32_16x16x32_bf16 v[72:75], v[226:229], v[202:205], v[72:75]
	v_mfma_f32_16x16x32_bf16 v[68:71], v[218:221], v[210:213], v[68:71]
	v_mfma_f32_16x16x32_bf16 v[64:67], v[226:229], v[210:213], v[64:67]
	s_barrier
	ds_read_b128 v[182:185], v171 offset:16384
	ds_read_b128 v[186:189], v171 offset:17408
	ds_read_b128 v[190:193], v171 offset:18432
	ds_read_b128 v[194:197], v171 offset:19456
	ds_read_b128 v[198:201], v171 offset:20480
	ds_read_b128 v[202:205], v171 offset:21504
	ds_read_b128 v[206:209], v171 offset:22528
	ds_read_b128 v[210:213], v171 offset:23552
	s_add_i32 s84, s65, s21
	s_mov_b32 m0, s84
	v_lshl_add_u64 v[158:159], s[54:55], 0, v[138:139]
	global_load_lds_dwordx4 v[158:159], off
	s_add_i32 m0, s84, 0x2000
	v_lshl_add_u64 v[230:231], s[54:55], 0, v[142:143]
	global_load_lds_dwordx4 v[230:231], off
	s_mov_b32 m0, s33
	v_lshl_add_u64 v[232:233], s[56:57], 0, v[136:137]
	global_load_lds_dwordx4 v[232:233], off
	s_mov_b32 m0, s35
	v_lshl_add_u64 v[234:235], s[56:57], 0, v[140:141]
	global_load_lds_dwordx4 v[234:235], off
	s_add_u32 s84, s54, 0xb0000
	s_addc_u32 s85, s55, 0
	s_add_i32 s86, s66, s21
	s_mov_b32 m0, s86
	v_lshl_add_u64 v[240:241], s[84:85], 0, v[138:139]
	global_load_lds_dwordx4 v[240:241], off
	s_add_i32 m0, s86, 0x2000
	v_lshl_add_u64 v[240:241], s[84:85], 0, v[142:143]
	global_load_lds_dwordx4 v[240:241], off
	s_waitcnt vmcnt(8) lgkmcnt(0)
	s_barrier
; #define PG8_STAGE(bufoff, gbase, voff) do { _Pragma("unroll") for (int _i = 0; _i < 2; ++_i) \
;         __builtin_amdgcn_global_load_lds((const unsigned*)((const char*)(gbase) + (voff)[_i]), (LAS unsigned*)(lds + (bufoff) + ldsw + _i * 8192), 16, 0, 0); } while (0)
; #define PG8_LDA(dst, b, h) do { _Pragma("unroll") for (int m = 0; m < 4; ++m) _Pragma("unroll") for (int k = 0; k < 2; ++k) dst[m][k] = *(const LAS bf16x8*)(lds + PG8_SA(b, h) + aoff + m * 2048 + k * 1024); } while (0)
; #define PG8_LDB(dst, b, h) do { _Pragma("unroll") for (int n = 0; n < 2; ++n) _Pragma("unroll") for (int k = 0; k < 2; ++k) dst[n][k] = *(const LAS bf16x8*)(lds + PG8_SB(b, h) + boff + n * 2048 + k * 1024); } while (0)
; #define PG8_MMA(ai, bj, At, Bt) do { __builtin_amdgcn_s_setprio(1); _Pragma("unroll") for (int m = 0; m < 4; ++m) _Pragma("unroll") for (int n = 0; n < 2; ++n) _Pragma("unroll") for (int k = 0; k < 2; ++k) \
;         acc[ai][bj][m][n] = __builtin_amdgcn_mfma_f32_16x16x32_bf16(Bt[n][k], At[m][k], acc[ai][bj][m][n], 0, 0, 0); __builtin_amdgcn_s_setprio(0); } while (0)
; #define PG8_WAIT_V(n) asm volatile("s_waitcnt vmcnt(" #n ")" ::: "memory")
; #define PG8_WAIT_L(n) asm volatile("s_waitcnt lgkmcnt(" #n ")" ::: "memory")
; #define PG8_BAR __builtin_amdgcn_s_barrier()
; #define PG8_SCHED __builtin_amdgcn_sched_barrier(0)
; template <class Epi>
; __device__ __forceinline__ void gemm_phase(LAS unsigned char* lds, const Gemm g, const StaticOrder& S, const Epi& E) {
;     ...
;             PG8_BAR; PG8_WAIT_L(0); PG8_MMA(1, 0, At, B0); PG8_BAR; PG8_SCHED;
;             PG8_STAGE(PG8_SB(0, 1), b2 + hstepB, voffB);
;             PG8_WAIT_V(6); PG8_BAR; PG8_MMA(1, 1, At, B1); PG8_BAR;
;             PG8_LDB(B0, 1, 0); PG8_SCHED; PG8_LDA(At, 1, 0); PG8_STAGE(PG8_SA(0, 1), a2 + hstepA, voffA);
;             PG8_WAIT_L(8); PG8_BAR; PG8_WAIT_L(0); PG8_MMA(0, 0, At, B0); PG8_BAR; PG8_SCHED;
;             PG8_LDB(B1, 1, 1); PG8_STAGE(PG8_SB(1, 0), b3, voffB);
;             PG8_BAR; PG8_WAIT_L(0); PG8_MMA(0, 1, At, B1); PG8_BAR;
	v_mfma_f32_16x16x32_bf16 v[60:63], v[150:153], v[182:185], v[60:63]
	v_mfma_f32_16x16x32_bf16 v[56:59], v[174:177], v[182:185], v[56:59]
	v_mfma_f32_16x16x32_bf16 v[52:55], v[150:153], v[190:193], v[52:55]
	v_mfma_f32_16x16x32_bf16 v[44:47], v[174:177], v[190:193], v[44:47]
	v_mfma_f32_16x16x32_bf16 v[36:39], v[150:153], v[198:201], v[36:39]
	v_mfma_f32_16x16x32_bf16 v[28:31], v[174:177], v[198:201], v[28:31]
	v_mfma_f32_16x16x32_bf16 v[20:23], v[150:153], v[206:209], v[20:23]
	v_mfma_f32_16x16x32_bf16 v[12:15], v[174:177], v[206:209], v[12:15]
	v_mfma_f32_16x16x32_bf16 v[60:63], v[154:157], v[186:189], v[60:63]
	v_mfma_f32_16x16x32_bf16 v[56:59], v[178:181], v[186:189], v[56:59]
	v_mfma_f32_16x16x32_bf16 v[52:55], v[154:157], v[194:197], v[52:55]
	v_mfma_f32_16x16x32_bf16 v[44:47], v[178:181], v[194:197], v[44:47]
	v_mfma_f32_16x16x32_bf16 v[36:39], v[154:157], v[202:205], v[36:39]
	v_mfma_f32_16x16x32_bf16 v[28:31], v[178:181], v[202:205], v[28:31]
	v_mfma_f32_16x16x32_bf16 v[20:23], v[154:157], v[210:213], v[20:23]
	v_mfma_f32_16x16x32_bf16 v[12:15], v[178:181], v[210:213], v[12:15]
	v_mfma_f32_16x16x32_bf16 v[48:51], v[214:217], v[182:185], v[48:51]
	v_mfma_f32_16x16x32_bf16 v[40:43], v[222:225], v[182:185], v[40:43]
	v_mfma_f32_16x16x32_bf16 v[32:35], v[214:217], v[190:193], v[32:35]
	v_mfma_f32_16x16x32_bf16 v[24:27], v[222:225], v[190:193], v[24:27]
	v_mfma_f32_16x16x32_bf16 v[16:19], v[214:217], v[198:201], v[16:19]
	v_mfma_f32_16x16x32_bf16 v[8:11], v[222:225], v[198:201], v[8:11]
	v_mfma_f32_16x16x32_bf16 v[4:7], v[214:217], v[206:209], v[4:7]
	v_mfma_f32_16x16x32_bf16 v[0:3], v[222:225], v[206:209], v[0:3]
	v_mfma_f32_16x16x32_bf16 v[48:51], v[218:221], v[186:189], v[48:51]
	v_mfma_f32_16x16x32_bf16 v[40:43], v[226:229], v[186:189], v[40:43]
	v_mfma_f32_16x16x32_bf16 v[32:35], v[218:221], v[194:197], v[32:35]
	v_mfma_f32_16x16x32_bf16 v[24:27], v[226:229], v[194:197], v[24:27]
	v_mfma_f32_16x16x32_bf16 v[16:19], v[218:221], v[202:205], v[16:19]
	v_mfma_f32_16x16x32_bf16 v[8:11], v[226:229], v[202:205], v[8:11]
	v_mfma_f32_16x16x32_bf16 v[4:7], v[218:221], v[210:213], v[4:7]
	v_mfma_f32_16x16x32_bf16 v[0:3], v[226:229], v[210:213], v[0:3]
	s_barrier
	s_add_i32 s84, 0, 0x18000
	v_add_u32_e32 v173, s84, v168
	ds_read_b128 v[150:153], v173
	ds_read_b128 v[154:157], v173 offset:1024
	ds_read_b128 v[174:177], v173 offset:2048
	ds_read_b128 v[178:181], v173 offset:3072
	ds_read_b128 v[182:185], v171 offset:32768
	ds_read_b128 v[186:189], v171 offset:33792
	ds_read_b128 v[190:193], v171 offset:34816
	ds_read_b128 v[194:197], v171 offset:35840
	ds_read_b128 v[198:201], v171 offset:36864
	ds_read_b128 v[202:205], v171 offset:37888
	ds_read_b128 v[206:209], v171 offset:38912
	ds_read_b128 v[210:213], v171 offset:39936
	s_add_i32 s98, 0, 0x1c000
	v_add_u32_e32 v246, s98, v168
	ds_read_b128 v[214:217], v246
	ds_read_b128 v[218:221], v246 offset:1024
	ds_read_b128 v[222:225], v246 offset:2048
	ds_read_b128 v[226:229], v246 offset:3072
	s_add_u32 s56, s56, 0x160000
	s_addc_u32 s57, s57, 0
	s_mov_b32 m0, s58
	v_lshl_add_u64 v[244:245], s[56:57], 0, v[136:137]
	global_load_lds_dwordx4 v[244:245], off
	s_mov_b32 m0, s59
	v_lshl_add_u64 v[244:245], s[56:57], 0, v[140:141]
	global_load_lds_dwordx4 v[244:245], off
	s_waitcnt vmcnt(8) lgkmcnt(0)
	s_barrier
	v_mfma_f32_16x16x32_bf16 v[124:127], v[150:153], v[182:185], v[124:127]
	v_mfma_f32_16x16x32_bf16 v[120:123], v[174:177], v[182:185], v[120:123]
	v_mfma_f32_16x16x32_bf16 v[116:119], v[150:153], v[190:193], v[116:119]
	v_mfma_f32_16x16x32_bf16 v[108:111], v[174:177], v[190:193], v[108:111]
	v_mfma_f32_16x16x32_bf16 v[100:103], v[150:153], v[198:201], v[100:103]
	v_mfma_f32_16x16x32_bf16 v[92:95], v[174:177], v[198:201], v[92:95]
	v_mfma_f32_16x16x32_bf16 v[84:87], v[150:153], v[206:209], v[84:87]
	v_mfma_f32_16x16x32_bf16 v[76:79], v[174:177], v[206:209], v[76:79]
	v_mfma_f32_16x16x32_bf16 v[124:127], v[154:157], v[186:189], v[124:127]
	v_mfma_f32_16x16x32_bf16 v[120:123], v[178:181], v[186:189], v[120:123]
	v_mfma_f32_16x16x32_bf16 v[116:119], v[154:157], v[194:197], v[116:119]
	v_mfma_f32_16x16x32_bf16 v[108:111], v[178:181], v[194:197], v[108:111]
	v_mfma_f32_16x16x32_bf16 v[100:103], v[154:157], v[202:205], v[100:103]
	v_mfma_f32_16x16x32_bf16 v[92:95], v[178:181], v[202:205], v[92:95]
	v_mfma_f32_16x16x32_bf16 v[84:87], v[154:157], v[210:213], v[84:87]
	v_mfma_f32_16x16x32_bf16 v[76:79], v[178:181], v[210:213], v[76:79]
	v_mfma_f32_16x16x32_bf16 v[112:115], v[214:217], v[182:185], v[112:115]
	v_mfma_f32_16x16x32_bf16 v[104:107], v[222:225], v[182:185], v[104:107]
	v_mfma_f32_16x16x32_bf16 v[96:99], v[214:217], v[190:193], v[96:99]
	v_mfma_f32_16x16x32_bf16 v[88:91], v[222:225], v[190:193], v[88:91]
	v_mfma_f32_16x16x32_bf16 v[80:83], v[214:217], v[198:201], v[80:83]
	v_mfma_f32_16x16x32_bf16 v[72:75], v[222:225], v[198:201], v[72:75]
	v_mfma_f32_16x16x32_bf16 v[68:71], v[214:217], v[206:209], v[68:71]
	v_mfma_f32_16x16x32_bf16 v[64:67], v[222:225], v[206:209], v[64:67]
	v_mfma_f32_16x16x32_bf16 v[112:115], v[218:221], v[186:189], v[112:115]
	v_mfma_f32_16x16x32_bf16 v[104:107], v[226:229], v[186:189], v[104:107]
	v_mfma_f32_16x16x32_bf16 v[96:99], v[218:221], v[194:197], v[96:99]
	v_mfma_f32_16x16x32_bf16 v[88:91], v[226:229], v[194:197], v[88:91]
	v_mfma_f32_16x16x32_bf16 v[80:83], v[218:221], v[202:205], v[80:83]
	v_mfma_f32_16x16x32_bf16 v[72:75], v[226:229], v[202:205], v[72:75]
	v_mfma_f32_16x16x32_bf16 v[68:71], v[218:221], v[210:213], v[68:71]
	v_mfma_f32_16x16x32_bf16 v[64:67], v[226:229], v[210:213], v[64:67]
	s_barrier
; #define PG8_STAGE(bufoff, gbase, voff) do { _Pragma("unroll") for (int _i = 0; _i < 2; ++_i) \
;         __builtin_amdgcn_global_load_lds((const unsigned*)((const char*)(gbase) + (voff)[_i]), (LAS unsigned*)(lds + (bufoff) + ldsw + _i * 8192), 16, 0, 0); } while (0)
; #define PG8_LDA(dst, b, h) do { _Pragma("unroll") for (int m = 0; m < 4; ++m) _Pragma("unroll") for (int k = 0; k < 2; ++k) dst[m][k] = *(const LAS bf16x8*)(lds + PG8_SA(b, h) + aoff + m * 2048 + k * 1024); } while (0)
; #define PG8_MMA(ai, bj, At, Bt) do { __builtin_amdgcn_s_setprio(1); _Pragma("unroll") for (int m = 0; m < 4; ++m) _Pragma("unroll") for (int n = 0; n < 2; ++n) _Pragma("unroll") for (int k = 0; k < 2; ++k) \
;         acc[ai][bj][m][n] = __builtin_amdgcn_mfma_f32_16x16x32_bf16(Bt[n][k], At[m][k], acc[ai][bj][m][n], 0, 0, 0); __builtin_amdgcn_s_setprio(0); } while (0)
; #define PG8_WAIT_V(n) asm volatile("s_waitcnt vmcnt(" #n ")" ::: "memory")
; #define PG8_WAIT_L(n) asm volatile("s_waitcnt lgkmcnt(" #n ")" ::: "memory")
; #define PG8_BAR __builtin_amdgcn_s_barrier()
; #define PG8_SCHED __builtin_amdgcn_sched_barrier(0)
; template <class Epi>
; __device__ __forceinline__ void gemm_phase(LAS unsigned char* lds, const Gemm g, const StaticOrder& S, const Epi& E) {
;     ...
;         for (int t = 0; t < nt; t += 2) {
;     ...
;             PG8_LDA(At, 1, 1); PG8_STAGE(PG8_SA(1, 0), a3, voffA);
;             PG8_BAR; PG8_WAIT_L(0); PG8_MMA(1, 0, At, B0); PG8_BAR; PG8_SCHED;
;             PG8_STAGE(PG8_SB(1, 1), b3 + hstepB, voffB);
;             PG8_WAIT_V(6); PG8_BAR; PG8_MMA(1, 1, At, B1); PG8_BAR;
	ds_read_b128 v[182:185], v171 offset:49152
	ds_read_b128 v[186:189], v171 offset:50176
	ds_read_b128 v[190:193], v171 offset:51200
	ds_read_b128 v[194:197], v171 offset:52224
	ds_read_b128 v[198:201], v171 offset:53248
	ds_read_b128 v[202:205], v171 offset:54272
	ds_read_b128 v[206:209], v171 offset:55296
	ds_read_b128 v[210:213], v171 offset:56320
	s_add_i32 s57, s84, s21
	s_mov_b32 m0, s57
	v_lshl_add_u64 v[158:159], v[158:159], 0, s[22:23]
	global_load_lds_dwordx4 v[158:159], off
	s_add_i32 m0, s57, 0x2000
	v_lshl_add_u64 v[158:159], v[230:231], 0, s[22:23]
	global_load_lds_dwordx4 v[158:159], off
	s_mov_b32 m0, s60
	v_lshl_add_u64 v[158:159], v[232:233], 0, s[22:23]
	global_load_lds_dwordx4 v[158:159], off
	s_mov_b32 m0, s61
	v_lshl_add_u64 v[158:159], v[234:235], 0, s[22:23]
	global_load_lds_dwordx4 v[158:159], off
	s_add_u32 s54, s54, 0xb0080
	s_addc_u32 s55, s55, 0
	s_add_i32 s56, s98, s21
	s_mov_b32 m0, s56
	v_lshl_add_u64 v[240:241], s[54:55], 0, v[138:139]
	global_load_lds_dwordx4 v[240:241], off
	s_add_i32 m0, s56, 0x2000
	v_lshl_add_u64 v[240:241], s[54:55], 0, v[142:143]
	global_load_lds_dwordx4 v[240:241], off
	s_waitcnt vmcnt(8) lgkmcnt(0)
	s_barrier
	v_mfma_f32_16x16x32_bf16 v[60:63], v[150:153], v[182:185], v[60:63]
	v_mfma_f32_16x16x32_bf16 v[56:59], v[174:177], v[182:185], v[56:59]
	v_mfma_f32_16x16x32_bf16 v[52:55], v[150:153], v[190:193], v[52:55]
	v_mfma_f32_16x16x32_bf16 v[44:47], v[174:177], v[190:193], v[44:47]
	v_mfma_f32_16x16x32_bf16 v[36:39], v[150:153], v[198:201], v[36:39]
	v_mfma_f32_16x16x32_bf16 v[28:31], v[174:177], v[198:201], v[28:31]
	v_mfma_f32_16x16x32_bf16 v[20:23], v[150:153], v[206:209], v[20:23]
	v_mfma_f32_16x16x32_bf16 v[12:15], v[174:177], v[206:209], v[12:15]
	v_mfma_f32_16x16x32_bf16 v[60:63], v[154:157], v[186:189], v[60:63]
	v_mfma_f32_16x16x32_bf16 v[56:59], v[178:181], v[186:189], v[56:59]
	v_mfma_f32_16x16x32_bf16 v[52:55], v[154:157], v[194:197], v[52:55]
	v_mfma_f32_16x16x32_bf16 v[44:47], v[178:181], v[194:197], v[44:47]
	v_mfma_f32_16x16x32_bf16 v[36:39], v[154:157], v[202:205], v[36:39]
	v_mfma_f32_16x16x32_bf16 v[28:31], v[178:181], v[202:205], v[28:31]
	v_mfma_f32_16x16x32_bf16 v[20:23], v[154:157], v[210:213], v[20:23]
	v_mfma_f32_16x16x32_bf16 v[12:15], v[178:181], v[210:213], v[12:15]
	v_mfma_f32_16x16x32_bf16 v[48:51], v[214:217], v[182:185], v[48:51]
	v_mfma_f32_16x16x32_bf16 v[40:43], v[222:225], v[182:185], v[40:43]
	v_mfma_f32_16x16x32_bf16 v[32:35], v[214:217], v[190:193], v[32:35]
	v_mfma_f32_16x16x32_bf16 v[24:27], v[222:225], v[190:193], v[24:27]
	v_mfma_f32_16x16x32_bf16 v[16:19], v[214:217], v[198:201], v[16:19]
	v_mfma_f32_16x16x32_bf16 v[8:11], v[222:225], v[198:201], v[8:11]
	v_mfma_f32_16x16x32_bf16 v[4:7], v[214:217], v[206:209], v[4:7]
	v_mfma_f32_16x16x32_bf16 v[0:3], v[222:225], v[206:209], v[0:3]
	v_mfma_f32_16x16x32_bf16 v[48:51], v[218:221], v[186:189], v[48:51]
	v_mfma_f32_16x16x32_bf16 v[40:43], v[226:229], v[186:189], v[40:43]
	v_mfma_f32_16x16x32_bf16 v[32:35], v[218:221], v[194:197], v[32:35]
	v_mfma_f32_16x16x32_bf16 v[24:27], v[226:229], v[194:197], v[24:27]
	v_mfma_f32_16x16x32_bf16 v[16:19], v[218:221], v[202:205], v[16:19]
	v_mfma_f32_16x16x32_bf16 v[8:11], v[226:229], v[202:205], v[8:11]
	v_mfma_f32_16x16x32_bf16 v[4:7], v[218:221], v[210:213], v[4:7]
	v_mfma_f32_16x16x32_bf16 v[0:3], v[226:229], v[210:213], v[0:3]
	s_add_u32 s46, s46, 0x100
	s_addc_u32 s47, s47, 0
	s_add_u32 s41, s41, 0x100
	s_addc_u32 s82, s82, 0
	s_cmp_ge_i32 s83, s81
	s_mov_b32 s54, s83
	s_barrier
	s_cbranch_scc0 .LBB0_910
;     __device__ __forceinline__ void operator()(const f32x4 (&acc)[2][2][4][2], const Unit& u, int wr, int wc, int fr, int fq) const {
;     ...
;         if (u.part) {
;             float* base = tailacc + (size_t)(u.part - 1) * slab - (size_t)tail_row0 * tail_ld;
; #pragma unroll
;             for (int ai = 0; ai < 2; ++ai)
; #pragma unroll
;                 for (int m = 0; m < 4; ++m) { float* rowp = base + (size_t)(row0 + ai * HALF + m * 16) * tail_ld + col0;
; #pragma unroll
;                     for (int bj = 0; bj < 2; ++bj)
; #pragma unroll
;                         for (int n = 0; n < 2; ++n) *(f32x4*)(rowp + bj * HALF + 4 * n) = acc[ai][bj][m][n]; }
;             return;
	v_lshl_add_u32 v158, s78, 8, v167
	v_lshl_or_b32 v150, s79, 8, v169
	v_or_b32_e32 v156, 16, v158
	v_or_b32_e32 v154, 32, v158
	v_or_b32_e32 v152, 48, v158
	s_cmp_lg_u32 s80, 0
	v_ashrrev_i32_e32 v151, 31, v150
	v_ashrrev_i32_e32 v159, 31, v158
	v_ashrrev_i32_e32 v157, 31, v156
	v_ashrrev_i32_e32 v155, 31, v154
	v_ashrrev_i32_e32 v153, 31, v152
	s_cbranch_scc0 .LBB0_913
	s_add_i32 s18, s80, -1
	s_lshl_b64 s[46:47], s[18:19], 21
	s_add_u32 s46, s92, s46
	s_addc_u32 s47, s93, s47
	v_lshl_add_u64 v[174:175], v[150:151], 2, s[46:47]
	s_brev_b32 s46, 63
	s_mov_b32 s47, -1
	v_lshl_add_u64 v[174:175], v[174:175], 0, s[46:47]
	v_lshlrev_b64 v[176:177], 12, v[158:159]
	v_lshlrev_b64 v[178:179], 12, v[156:157]
	v_lshl_add_u64 v[176:177], v[174:175], 0, v[176:177]
	v_lshl_add_u64 v[178:179], v[174:175], 0, v[178:179]
	global_store_dwordx4 v[176:177], v[124:127], off
	global_store_dwordx4 v[176:177], v[120:123], off offset:16
	global_store_dwordx4 v[176:177], v[112:115], off offset:512
	global_store_dwordx4 v[176:177], v[104:107], off offset:528
	global_store_dwordx4 v[178:179], v[116:119], off
	global_store_dwordx4 v[178:179], v[108:111], off offset:16
	global_store_dwordx4 v[178:179], v[96:99], off offset:512
	global_store_dwordx4 v[178:179], v[88:91], off offset:528
	v_lshlrev_b64 v[178:179], 12, v[154:155]
	v_lshl_add_u64 v[178:179], v[174:175], 0, v[178:179]
	global_store_dwordx4 v[178:179], v[100:103], off
	global_store_dwordx4 v[178:179], v[92:95], off offset:16
	global_store_dwordx4 v[178:179], v[80:83], off offset:512
	global_store_dwordx4 v[178:179], v[72:75], off offset:528
	v_lshlrev_b64 v[178:179], 12, v[152:153]
	s_mov_b32 s18, 0x80000
	v_lshl_add_u64 v[174:175], v[174:175], 0, v[178:179]
	v_add_co_u32_e32 v178, vcc, s18, v176
	s_mov_b64 s[46:47], 0x80000
	s_nop 0
	v_addc_co_u32_e32 v179, vcc, 0, v177, vcc
	global_store_dwordx4 v[174:175], v[84:87], off
	global_store_dwordx4 v[174:175], v[76:79], off offset:16
	global_store_dwordx4 v[174:175], v[68:71], off offset:512
	global_store_dwordx4 v[174:175], v[64:67], off offset:528
	v_lshl_add_u64 v[174:175], v[176:177], 0, s[46:47]
	global_store_dwordx4 v[178:179], v[60:63], off
	global_store_dwordx4 v[174:175], v[56:59], off offset:16
	global_store_dwordx4 v[174:175], v[48:51], off offset:512
	global_store_dwordx4 v[174:175], v[40:43], off offset:528
	v_add_co_u32_e32 v178, vcc, s67, v176
	s_mov_b64 s[46:47], 0x90000
	s_nop 0
	v_addc_co_u32_e32 v179, vcc, 0, v177, vcc
	v_lshl_add_u64 v[174:175], v[176:177], 0, s[46:47]
	global_store_dwordx4 v[178:179], v[52:55], off
	global_store_dwordx4 v[174:175], v[44:47], off offset:16
	global_store_dwordx4 v[174:175], v[32:35], off offset:512
	global_store_dwordx4 v[174:175], v[24:27], off offset:528
	v_add_co_u32_e32 v178, vcc, s68, v176
	v_lshl_add_u64 v[174:175], v[176:177], 0, s[24:25]
	s_nop 0
	v_addc_co_u32_e32 v179, vcc, 0, v177, vcc
	s_mov_b64 s[46:47], 0xb0000
	global_store_dwordx4 v[178:179], v[36:39], off
	global_store_dwordx4 v[174:175], v[28:31], off offset:16
	global_store_dwordx4 v[174:175], v[16:19], off offset:512
	global_store_dwordx4 v[174:175], v[8:11], off offset:528
	v_lshl_add_u64 v[174:175], v[176:177], 0, s[46:47]
	v_add_co_u32_e32 v176, vcc, 0xb0000, v176
	s_nop 1
	v_addc_co_u32_e32 v177, vcc, 0, v177, vcc
	global_store_dwordx4 v[176:177], v[20:23], off
	global_store_dwordx4 v[174:175], v[12:15], off offset:16
	global_store_dwordx4 v[174:175], v[4:7], off offset:512
	global_store_dwordx4 v[174:175], v[0:3], off offset:528
	s_cbranch_execnz .LBB0_895
	s_branch .LBB0_894

; #define PG8_STAGE(bufoff, gbase, voff) do { _Pragma("unroll") for (int _i = 0; _i < 2; ++_i) \
;         __builtin_amdgcn_global_load_lds((const unsigned*)((const char*)(gbase) + (voff)[_i]), (LAS unsigned*)(lds + (bufoff) + ldsw + _i * 8192), 16, 0, 0); } while (0)
; #define PG8_LDA(dst, b, h) do { _Pragma("unroll") for (int m = 0; m < 4; ++m) _Pragma("unroll") for (int k = 0; k < 2; ++k) dst[m][k] = *(const LAS bf16x8*)(lds + PG8_SA(b, h) + aoff + m * 2048 + k * 1024); } while (0)
; #define PG8_LDB(dst, b, h) do { _Pragma("unroll") for (int n = 0; n < 2; ++n) _Pragma("unroll") for (int k = 0; k < 2; ++k) dst[n][k] = *(const LAS bf16x8*)(lds + PG8_SB(b, h) + boff + n * 2048 + k * 1024); } while (0)
; #define PG8_MMA(ai, bj, At, Bt) do { __builtin_amdgcn_s_setprio(1); _Pragma("unroll") for (int m = 0; m < 4; ++m) _Pragma("unroll") for (int n = 0; n < 2; ++n) _Pragma("unroll") for (int k = 0; k < 2; ++k) \
;         acc[ai][bj][m][n] = __builtin_amdgcn_mfma_f32_16x16x32_bf16(Bt[n][k], At[m][k], acc[ai][bj][m][n], 0, 0, 0); __builtin_amdgcn_s_setprio(0); } while (0)
; #define PG8_WAIT_V(n) asm volatile("s_waitcnt vmcnt(" #n ")" ::: "memory")
; #define PG8_WAIT_L(n) asm volatile("s_waitcnt lgkmcnt(" #n ")" ::: "memory")
; template <class Epi>
; __device__ __forceinline__ void gemm_phase(LAS unsigned char* lds, const Gemm g, const StaticOrder& S, const Epi& E) {
;     ...
;         for (int t = 0; t < nt; t += 2) {
;             const bool last = (t == nt - 2);
;             const char* a1 = cA + (size_t)(t + 1) * kstep;
;             const char* a2 = last ? nA : cA + (size_t)(t + 2) * kstep; const char* b2 = last ? nB : cB + (size_t)(t + 2) * kstep;
;             const char* a3 = a2 + kstep; const char* b3 = b2 + kstep;
;             PG8_LDB(B0, 0, 0); PG8_SCHED; PG8_LDA(At, 0, 0); PG8_STAGE(PG8_SA(1, 1), a1 + hstepA, voffA);
;             PG8_WAIT_L(8); PG8_BAR; PG8_WAIT_L(0); PG8_MMA(0, 0, At, B0); PG8_BAR; PG8_SCHED;
;             PG8_LDB(B1, 0, 1); PG8_STAGE(PG8_SB(0, 0), b2, voffB);
;             PG8_BAR; PG8_WAIT_L(0); PG8_MMA(0, 1, At, B1); PG8_BAR;
;             PG8_LDA(At, 0, 1); PG8_STAGE(PG8_SA(0, 0), a2, voffA);
;             PG8_BAR; PG8_WAIT_L(0); PG8_MMA(1, 0, At, B0); PG8_BAR; PG8_SCHED;
;             PG8_STAGE(PG8_SB(0, 1), b2 + hstepB, voffB);
;             PG8_WAIT_V(6); PG8_BAR; PG8_MMA(1, 1, At, B1); PG8_BAR;
.LBB0_1146:
	s_add_i32 s77, s45, 2
	s_add_u32 s54, s50, 0xfffc0080
	s_addc_u32 s55, s51, -1
	s_cmp_eq_u32 s39, s45
	s_cselect_b32 s57, s49, s55
	s_cselect_b32 s56, s48, s54
	s_cselect_b32 s55, s1, s43
	s_cselect_b32 s54, s0, s41
	ds_read_b128 v[150:153], v129
	ds_read_b128 v[154:157], v129 offset:1024
	ds_read_b128 v[158:161], v129 offset:2048
	ds_read_b128 v[166:169], v129 offset:3072
	ds_read_b128 v[170:173], v163
	ds_read_b128 v[174:177], v163 offset:1024
	ds_read_b128 v[178:181], v163 offset:2048
	ds_read_b128 v[182:185], v163 offset:3072
	ds_read_b128 v[186:189], v163 offset:4096
	ds_read_b128 v[190:193], v163 offset:5120
	ds_read_b128 v[194:197], v163 offset:6144
	ds_read_b128 v[198:201], v163 offset:7168
	ds_read_b128 v[202:205], v164
	ds_read_b128 v[206:209], v164 offset:1024
	ds_read_b128 v[210:213], v164 offset:2048
	ds_read_b128 v[214:217], v164 offset:3072
	s_add_i32 m0, s33, 0xc000
	v_lshl_add_u64 v[242:243], s[50:51], 0, v[144:145]
	global_load_lds_dwordx4 v[242:243], off
	s_add_i32 m0, s33, 0xe000
	v_lshl_add_u64 v[242:243], s[50:51], 0, v[146:147]
	global_load_lds_dwordx4 v[242:243], off
	s_waitcnt vmcnt(8) lgkmcnt(0)
	s_barrier
	v_mfma_f32_16x16x32_bf16 v[124:127], v[150:153], v[170:173], v[124:127]
	v_mfma_f32_16x16x32_bf16 v[120:123], v[158:161], v[170:173], v[120:123]
	v_mfma_f32_16x16x32_bf16 v[116:119], v[150:153], v[178:181], v[116:119]
	v_mfma_f32_16x16x32_bf16 v[108:111], v[158:161], v[178:181], v[108:111]
	v_mfma_f32_16x16x32_bf16 v[100:103], v[150:153], v[186:189], v[100:103]
	v_mfma_f32_16x16x32_bf16 v[92:95], v[158:161], v[186:189], v[92:95]
	v_mfma_f32_16x16x32_bf16 v[84:87], v[150:153], v[194:197], v[84:87]
	v_mfma_f32_16x16x32_bf16 v[76:79], v[158:161], v[194:197], v[76:79]
	v_mfma_f32_16x16x32_bf16 v[124:127], v[154:157], v[174:177], v[124:127]
	v_mfma_f32_16x16x32_bf16 v[120:123], v[166:169], v[174:177], v[120:123]
	v_mfma_f32_16x16x32_bf16 v[116:119], v[154:157], v[182:185], v[116:119]
	v_mfma_f32_16x16x32_bf16 v[108:111], v[166:169], v[182:185], v[108:111]
	v_mfma_f32_16x16x32_bf16 v[100:103], v[154:157], v[190:193], v[100:103]
	v_mfma_f32_16x16x32_bf16 v[92:95], v[166:169], v[190:193], v[92:95]
	v_mfma_f32_16x16x32_bf16 v[84:87], v[154:157], v[198:201], v[84:87]
	v_mfma_f32_16x16x32_bf16 v[76:79], v[166:169], v[198:201], v[76:79]
	v_mfma_f32_16x16x32_bf16 v[112:115], v[202:205], v[170:173], v[112:115]
	v_mfma_f32_16x16x32_bf16 v[104:107], v[210:213], v[170:173], v[104:107]
	v_mfma_f32_16x16x32_bf16 v[96:99], v[202:205], v[178:181], v[96:99]
	v_mfma_f32_16x16x32_bf16 v[88:91], v[210:213], v[178:181], v[88:91]
	v_mfma_f32_16x16x32_bf16 v[80:83], v[202:205], v[186:189], v[80:83]
	v_mfma_f32_16x16x32_bf16 v[72:75], v[210:213], v[186:189], v[72:75]
	v_mfma_f32_16x16x32_bf16 v[68:71], v[202:205], v[194:197], v[68:71]
	v_mfma_f32_16x16x32_bf16 v[64:67], v[210:213], v[194:197], v[64:67]
	v_mfma_f32_16x16x32_bf16 v[112:115], v[206:209], v[174:177], v[112:115]
	v_mfma_f32_16x16x32_bf16 v[104:107], v[214:217], v[174:177], v[104:107]
	v_mfma_f32_16x16x32_bf16 v[96:99], v[206:209], v[182:185], v[96:99]
	v_mfma_f32_16x16x32_bf16 v[88:91], v[214:217], v[182:185], v[88:91]
	v_mfma_f32_16x16x32_bf16 v[80:83], v[206:209], v[190:193], v[80:83]
	v_mfma_f32_16x16x32_bf16 v[72:75], v[214:217], v[190:193], v[72:75]
	v_mfma_f32_16x16x32_bf16 v[68:71], v[206:209], v[198:201], v[68:71]
	v_mfma_f32_16x16x32_bf16 v[64:67], v[214:217], v[198:201], v[64:67]
	s_barrier
	ds_read_b128 v[170:173], v163 offset:16384
	ds_read_b128 v[174:177], v163 offset:17408
	ds_read_b128 v[178:181], v163 offset:18432
	ds_read_b128 v[182:185], v163 offset:19456
	ds_read_b128 v[186:189], v163 offset:20480
	ds_read_b128 v[190:193], v163 offset:21504
	ds_read_b128 v[194:197], v163 offset:22528
	ds_read_b128 v[198:201], v163 offset:23552
	s_add_i32 s45, s66, s21
	s_mov_b32 m0, s45
	v_lshl_add_u64 v[218:219], s[54:55], 0, v[138:139]
	global_load_lds_dwordx4 v[218:219], off
	s_add_i32 m0, s45, 0x2000
	v_lshl_add_u64 v[220:221], s[54:55], 0, v[142:143]
	global_load_lds_dwordx4 v[220:221], off
	s_mov_b32 m0, s33
	v_lshl_add_u64 v[222:223], s[56:57], 0, v[136:137]
	global_load_lds_dwordx4 v[222:223], off
	s_mov_b32 m0, s35
	v_lshl_add_u64 v[224:225], s[56:57], 0, v[140:141]
	global_load_lds_dwordx4 v[224:225], off
	s_add_u32 s78, s54, 0x40000
	s_addc_u32 s79, s55, 0
	s_add_i32 s45, s67, s21
	s_mov_b32 m0, s45
	v_lshl_add_u64 v[240:241], s[78:79], 0, v[138:139]
	global_load_lds_dwordx4 v[240:241], off
	s_add_i32 m0, s45, 0x2000
	v_lshl_add_u64 v[240:241], s[78:79], 0, v[142:143]
	global_load_lds_dwordx4 v[240:241], off
	s_waitcnt vmcnt(8) lgkmcnt(0)
	s_barrier
; #define PG8_STAGE(bufoff, gbase, voff) do { _Pragma("unroll") for (int _i = 0; _i < 2; ++_i) \
;         __builtin_amdgcn_global_load_lds((const unsigned*)((const char*)(gbase) + (voff)[_i]), (LAS unsigned*)(lds + (bufoff) + ldsw + _i * 8192), 16, 0, 0); } while (0)
; #define PG8_LDA(dst, b, h) do { _Pragma("unroll") for (int m = 0; m < 4; ++m) _Pragma("unroll") for (int k = 0; k < 2; ++k) dst[m][k] = *(const LAS bf16x8*)(lds + PG8_SA(b, h) + aoff + m * 2048 + k * 1024); } while (0)
; #define PG8_LDB(dst, b, h) do { _Pragma("unroll") for (int n = 0; n < 2; ++n) _Pragma("unroll") for (int k = 0; k < 2; ++k) dst[n][k] = *(const LAS bf16x8*)(lds + PG8_SB(b, h) + boff + n * 2048 + k * 1024); } while (0)
; #define PG8_MMA(ai, bj, At, Bt) do { __builtin_amdgcn_s_setprio(1); _Pragma("unroll") for (int m = 0; m < 4; ++m) _Pragma("unroll") for (int n = 0; n < 2; ++n) _Pragma("unroll") for (int k = 0; k < 2; ++k) \
;         acc[ai][bj][m][n] = __builtin_amdgcn_mfma_f32_16x16x32_bf16(Bt[n][k], At[m][k], acc[ai][bj][m][n], 0, 0, 0); __builtin_amdgcn_s_setprio(0); } while (0)
; #define PG8_WAIT_V(n) asm volatile("s_waitcnt vmcnt(" #n ")" ::: "memory")
; #define PG8_WAIT_L(n) asm volatile("s_waitcnt lgkmcnt(" #n ")" ::: "memory")
; #define PG8_BAR __builtin_amdgcn_s_barrier()
; #define PG8_SCHED __builtin_amdgcn_sched_barrier(0)
; template <class Epi>
; __device__ __forceinline__ void gemm_phase(LAS unsigned char* lds, const Gemm g, const StaticOrder& S, const Epi& E) {
;     ...
;             PG8_BAR; PG8_WAIT_L(0); PG8_MMA(0, 1, At, B1); PG8_BAR;
;             PG8_LDA(At, 0, 1); PG8_STAGE(PG8_SA(0, 0), a2, voffA);
;             PG8_BAR; PG8_WAIT_L(0); PG8_MMA(1, 0, At, B0); PG8_BAR; PG8_SCHED;
;             PG8_STAGE(PG8_SB(0, 1), b2 + hstepB, voffB);
;             PG8_WAIT_V(6); PG8_BAR; PG8_MMA(1, 1, At, B1); PG8_BAR;
;             PG8_LDB(B0, 1, 0); PG8_SCHED; PG8_LDA(At, 1, 0); PG8_STAGE(PG8_SA(0, 1), a2 + hstepA, voffA);
;             PG8_WAIT_L(8); PG8_BAR; PG8_WAIT_L(0); PG8_MMA(0, 0, At, B0); PG8_BAR; PG8_SCHED;
	v_mfma_f32_16x16x32_bf16 v[60:63], v[150:153], v[170:173], v[60:63]
	v_mfma_f32_16x16x32_bf16 v[56:59], v[158:161], v[170:173], v[56:59]
	v_mfma_f32_16x16x32_bf16 v[52:55], v[150:153], v[178:181], v[52:55]
	v_mfma_f32_16x16x32_bf16 v[44:47], v[158:161], v[178:181], v[44:47]
	v_mfma_f32_16x16x32_bf16 v[36:39], v[150:153], v[186:189], v[36:39]
	v_mfma_f32_16x16x32_bf16 v[28:31], v[158:161], v[186:189], v[28:31]
	v_mfma_f32_16x16x32_bf16 v[20:23], v[150:153], v[194:197], v[20:23]
	v_mfma_f32_16x16x32_bf16 v[12:15], v[158:161], v[194:197], v[12:15]
	v_mfma_f32_16x16x32_bf16 v[60:63], v[154:157], v[174:177], v[60:63]
	v_mfma_f32_16x16x32_bf16 v[56:59], v[166:169], v[174:177], v[56:59]
	v_mfma_f32_16x16x32_bf16 v[52:55], v[154:157], v[182:185], v[52:55]
	v_mfma_f32_16x16x32_bf16 v[44:47], v[166:169], v[182:185], v[44:47]
	v_mfma_f32_16x16x32_bf16 v[36:39], v[154:157], v[190:193], v[36:39]
	v_mfma_f32_16x16x32_bf16 v[28:31], v[166:169], v[190:193], v[28:31]
	v_mfma_f32_16x16x32_bf16 v[20:23], v[154:157], v[198:201], v[20:23]
	v_mfma_f32_16x16x32_bf16 v[12:15], v[166:169], v[198:201], v[12:15]
	v_mfma_f32_16x16x32_bf16 v[48:51], v[202:205], v[170:173], v[48:51]
	v_mfma_f32_16x16x32_bf16 v[40:43], v[210:213], v[170:173], v[40:43]
	v_mfma_f32_16x16x32_bf16 v[32:35], v[202:205], v[178:181], v[32:35]
	v_mfma_f32_16x16x32_bf16 v[24:27], v[210:213], v[178:181], v[24:27]
	v_mfma_f32_16x16x32_bf16 v[16:19], v[202:205], v[186:189], v[16:19]
	v_mfma_f32_16x16x32_bf16 v[8:11], v[210:213], v[186:189], v[8:11]
	v_mfma_f32_16x16x32_bf16 v[4:7], v[202:205], v[194:197], v[4:7]
	v_mfma_f32_16x16x32_bf16 v[0:3], v[210:213], v[194:197], v[0:3]
	v_mfma_f32_16x16x32_bf16 v[48:51], v[206:209], v[174:177], v[48:51]
	v_mfma_f32_16x16x32_bf16 v[40:43], v[214:217], v[174:177], v[40:43]
	v_mfma_f32_16x16x32_bf16 v[32:35], v[206:209], v[182:185], v[32:35]
	v_mfma_f32_16x16x32_bf16 v[24:27], v[214:217], v[182:185], v[24:27]
	v_mfma_f32_16x16x32_bf16 v[16:19], v[206:209], v[190:193], v[16:19]
	v_mfma_f32_16x16x32_bf16 v[8:11], v[214:217], v[190:193], v[8:11]
	v_mfma_f32_16x16x32_bf16 v[4:7], v[206:209], v[198:201], v[4:7]
	v_mfma_f32_16x16x32_bf16 v[0:3], v[214:217], v[198:201], v[0:3]
	s_barrier
	s_add_i32 s45, 0, 0x18000
	v_add_u32_e32 v165, s45, v135
	ds_read_b128 v[150:153], v165
	ds_read_b128 v[154:157], v165 offset:1024
	ds_read_b128 v[158:161], v165 offset:2048
	ds_read_b128 v[166:169], v165 offset:3072
	ds_read_b128 v[170:173], v163 offset:32768
	ds_read_b128 v[174:177], v163 offset:33792
	ds_read_b128 v[178:181], v163 offset:34816
	ds_read_b128 v[182:185], v163 offset:35840
	ds_read_b128 v[186:189], v163 offset:36864
	ds_read_b128 v[190:193], v163 offset:37888
	ds_read_b128 v[194:197], v163 offset:38912
	ds_read_b128 v[198:201], v163 offset:39936
	s_add_i32 s98, 0, 0x1c000
	v_add_u32_e32 v246, s98, v135
	ds_read_b128 v[202:205], v246
	ds_read_b128 v[206:209], v246 offset:1024
	ds_read_b128 v[210:213], v246 offset:2048
	ds_read_b128 v[214:217], v246 offset:3072
	s_add_u32 s56, s56, 0x40000
	s_addc_u32 s57, s57, 0
	s_mov_b32 m0, s58
	v_lshl_add_u64 v[244:245], s[56:57], 0, v[136:137]
	global_load_lds_dwordx4 v[244:245], off
	s_mov_b32 m0, s59
	v_lshl_add_u64 v[244:245], s[56:57], 0, v[140:141]
	global_load_lds_dwordx4 v[244:245], off
	s_waitcnt vmcnt(8) lgkmcnt(0)
	s_barrier
	v_mfma_f32_16x16x32_bf16 v[124:127], v[150:153], v[170:173], v[124:127]
	v_mfma_f32_16x16x32_bf16 v[120:123], v[158:161], v[170:173], v[120:123]
	v_mfma_f32_16x16x32_bf16 v[116:119], v[150:153], v[178:181], v[116:119]
	v_mfma_f32_16x16x32_bf16 v[108:111], v[158:161], v[178:181], v[108:111]
	v_mfma_f32_16x16x32_bf16 v[100:103], v[150:153], v[186:189], v[100:103]
	v_mfma_f32_16x16x32_bf16 v[92:95], v[158:161], v[186:189], v[92:95]
	v_mfma_f32_16x16x32_bf16 v[84:87], v[150:153], v[194:197], v[84:87]
	v_mfma_f32_16x16x32_bf16 v[76:79], v[158:161], v[194:197], v[76:79]
	v_mfma_f32_16x16x32_bf16 v[124:127], v[154:157], v[174:177], v[124:127]
	v_mfma_f32_16x16x32_bf16 v[120:123], v[166:169], v[174:177], v[120:123]
	v_mfma_f32_16x16x32_bf16 v[116:119], v[154:157], v[182:185], v[116:119]
	v_mfma_f32_16x16x32_bf16 v[108:111], v[166:169], v[182:185], v[108:111]
	v_mfma_f32_16x16x32_bf16 v[100:103], v[154:157], v[190:193], v[100:103]
	v_mfma_f32_16x16x32_bf16 v[92:95], v[166:169], v[190:193], v[92:95]
	v_mfma_f32_16x16x32_bf16 v[84:87], v[154:157], v[198:201], v[84:87]
	v_mfma_f32_16x16x32_bf16 v[76:79], v[166:169], v[198:201], v[76:79]
	v_mfma_f32_16x16x32_bf16 v[112:115], v[202:205], v[170:173], v[112:115]
	v_mfma_f32_16x16x32_bf16 v[104:107], v[210:213], v[170:173], v[104:107]
	v_mfma_f32_16x16x32_bf16 v[96:99], v[202:205], v[178:181], v[96:99]
	v_mfma_f32_16x16x32_bf16 v[88:91], v[210:213], v[178:181], v[88:91]
	v_mfma_f32_16x16x32_bf16 v[80:83], v[202:205], v[186:189], v[80:83]
	v_mfma_f32_16x16x32_bf16 v[72:75], v[210:213], v[186:189], v[72:75]
	v_mfma_f32_16x16x32_bf16 v[68:71], v[202:205], v[194:197], v[68:71]
	v_mfma_f32_16x16x32_bf16 v[64:67], v[210:213], v[194:197], v[64:67]
	v_mfma_f32_16x16x32_bf16 v[112:115], v[206:209], v[174:177], v[112:115]
	v_mfma_f32_16x16x32_bf16 v[104:107], v[214:217], v[174:177], v[104:107]
	v_mfma_f32_16x16x32_bf16 v[96:99], v[206:209], v[182:185], v[96:99]
	v_mfma_f32_16x16x32_bf16 v[88:91], v[214:217], v[182:185], v[88:91]
	v_mfma_f32_16x16x32_bf16 v[80:83], v[206:209], v[190:193], v[80:83]
	v_mfma_f32_16x16x32_bf16 v[72:75], v[214:217], v[190:193], v[72:75]
	v_mfma_f32_16x16x32_bf16 v[68:71], v[206:209], v[198:201], v[68:71]
	v_mfma_f32_16x16x32_bf16 v[64:67], v[214:217], v[198:201], v[64:67]
	s_barrier
; #define PG8_STAGE(bufoff, gbase, voff) do { _Pragma("unroll") for (int _i = 0; _i < 2; ++_i) \
;         __builtin_amdgcn_global_load_lds((const unsigned*)((const char*)(gbase) + (voff)[_i]), (LAS unsigned*)(lds + (bufoff) + ldsw + _i * 8192), 16, 0, 0); } while (0)
; #define PG8_LDA(dst, b, h) do { _Pragma("unroll") for (int m = 0; m < 4; ++m) _Pragma("unroll") for (int k = 0; k < 2; ++k) dst[m][k] = *(const LAS bf16x8*)(lds + PG8_SA(b, h) + aoff + m * 2048 + k * 1024); } while (0)
; #define PG8_LDB(dst, b, h) do { _Pragma("unroll") for (int n = 0; n < 2; ++n) _Pragma("unroll") for (int k = 0; k < 2; ++k) dst[n][k] = *(const LAS bf16x8*)(lds + PG8_SB(b, h) + boff + n * 2048 + k * 1024); } while (0)
; #define PG8_MMA(ai, bj, At, Bt) do { __builtin_amdgcn_s_setprio(1); _Pragma("unroll") for (int m = 0; m < 4; ++m) _Pragma("unroll") for (int n = 0; n < 2; ++n) _Pragma("unroll") for (int k = 0; k < 2; ++k) \
;         acc[ai][bj][m][n] = __builtin_amdgcn_mfma_f32_16x16x32_bf16(Bt[n][k], At[m][k], acc[ai][bj][m][n], 0, 0, 0); __builtin_amdgcn_s_setprio(0); } while (0)
;     __device__ __forceinline__ void operator()(const f32x4 (&acc)[2][2][4][2], const Unit& u, int wr, int wc, int fr, int fq) const {
;     ...
;         if (u.part) {
;             float* base = tailacc + (size_t)(u.part - 1) * slab - (size_t)tail_row0 * tail_ld;
; #pragma unroll
;             for (int ai = 0; ai < 2; ++ai)
; #pragma unroll
;                 for (int m = 0; m < 4; ++m) { float* rowp = base + (size_t)(row0 + ai * HALF + m * 16) * tail_ld + col0;
; #pragma unroll
;                     for (int bj = 0; bj < 2; ++bj)
; #pragma unroll
;                         for (int n = 0; n < 2; ++n) *(f32x4*)(rowp + bj * HALF + 4 * n) = acc[ai][bj][m][n]; }
; template <class Epi>
; __device__ __forceinline__ void gemm_phase(LAS unsigned char* lds, const Gemm g, const StaticOrder& S, const Epi& E) {
;     ...
;             PG8_LDB(B1, 1, 1); PG8_STAGE(PG8_SB(1, 0), b3, voffB);
;             PG8_BAR; PG8_WAIT_L(0); PG8_MMA(0, 1, At, B1); PG8_BAR;
;             PG8_LDA(At, 1, 1); PG8_STAGE(PG8_SA(1, 0), a3, voffA);
;             PG8_BAR; PG8_WAIT_L(0); PG8_MMA(1, 0, At, B0); PG8_BAR; PG8_SCHED;
;             PG8_STAGE(PG8_SB(1, 1), b3 + hstepB, voffB);
;             PG8_WAIT_V(6); PG8_BAR; PG8_MMA(1, 1, At, B1); PG8_BAR;
;         }
;         E(acc, cur, wr, wc, fr, fq);
	ds_read_b128 v[170:173], v163 offset:49152
	ds_read_b128 v[174:177], v163 offset:50176
	ds_read_b128 v[178:181], v163 offset:51200
	ds_read_b128 v[182:185], v163 offset:52224
	ds_read_b128 v[186:189], v163 offset:53248
	ds_read_b128 v[190:193], v163 offset:54272
	ds_read_b128 v[194:197], v163 offset:55296
	ds_read_b128 v[198:201], v163 offset:56320
	s_add_i32 s45, s45, s21
	s_mov_b32 m0, s45
	v_lshl_add_u64 v[218:219], v[218:219], 0, s[12:13]
	global_load_lds_dwordx4 v[218:219], off
	s_add_i32 m0, s45, 0x2000
	v_lshl_add_u64 v[218:219], v[220:221], 0, s[12:13]
	global_load_lds_dwordx4 v[218:219], off
	s_mov_b32 m0, s60
	v_lshl_add_u64 v[218:219], v[222:223], 0, s[12:13]
	global_load_lds_dwordx4 v[218:219], off
	s_mov_b32 m0, s61
	v_lshl_add_u64 v[218:219], v[224:225], 0, s[12:13]
	global_load_lds_dwordx4 v[218:219], off
	s_add_u32 s54, s54, 0x40080
	s_addc_u32 s55, s55, 0
	s_add_i32 s45, s98, s21
	s_mov_b32 m0, s45
	v_lshl_add_u64 v[240:241], s[54:55], 0, v[138:139]
	global_load_lds_dwordx4 v[240:241], off
	s_add_i32 m0, s45, 0x2000
	v_lshl_add_u64 v[240:241], s[54:55], 0, v[142:143]
	global_load_lds_dwordx4 v[240:241], off
	s_waitcnt vmcnt(8) lgkmcnt(0)
	s_barrier
	v_mfma_f32_16x16x32_bf16 v[60:63], v[150:153], v[170:173], v[60:63]
	v_mfma_f32_16x16x32_bf16 v[56:59], v[158:161], v[170:173], v[56:59]
	v_mfma_f32_16x16x32_bf16 v[52:55], v[150:153], v[178:181], v[52:55]
	v_mfma_f32_16x16x32_bf16 v[44:47], v[158:161], v[178:181], v[44:47]
	v_mfma_f32_16x16x32_bf16 v[36:39], v[150:153], v[186:189], v[36:39]
	v_mfma_f32_16x16x32_bf16 v[28:31], v[158:161], v[186:189], v[28:31]
	v_mfma_f32_16x16x32_bf16 v[20:23], v[150:153], v[194:197], v[20:23]
	v_mfma_f32_16x16x32_bf16 v[12:15], v[158:161], v[194:197], v[12:15]
	v_mfma_f32_16x16x32_bf16 v[60:63], v[154:157], v[174:177], v[60:63]
	v_mfma_f32_16x16x32_bf16 v[56:59], v[166:169], v[174:177], v[56:59]
	v_mfma_f32_16x16x32_bf16 v[52:55], v[154:157], v[182:185], v[52:55]
	v_mfma_f32_16x16x32_bf16 v[44:47], v[166:169], v[182:185], v[44:47]
	v_mfma_f32_16x16x32_bf16 v[36:39], v[154:157], v[190:193], v[36:39]
	v_mfma_f32_16x16x32_bf16 v[28:31], v[166:169], v[190:193], v[28:31]
	v_mfma_f32_16x16x32_bf16 v[20:23], v[154:157], v[198:201], v[20:23]
	v_mfma_f32_16x16x32_bf16 v[12:15], v[166:169], v[198:201], v[12:15]
	v_mfma_f32_16x16x32_bf16 v[48:51], v[202:205], v[170:173], v[48:51]
	v_mfma_f32_16x16x32_bf16 v[40:43], v[210:213], v[170:173], v[40:43]
	v_mfma_f32_16x16x32_bf16 v[32:35], v[202:205], v[178:181], v[32:35]
	v_mfma_f32_16x16x32_bf16 v[24:27], v[210:213], v[178:181], v[24:27]
	v_mfma_f32_16x16x32_bf16 v[16:19], v[202:205], v[186:189], v[16:19]
	v_mfma_f32_16x16x32_bf16 v[8:11], v[210:213], v[186:189], v[8:11]
	v_mfma_f32_16x16x32_bf16 v[4:7], v[202:205], v[194:197], v[4:7]
	v_mfma_f32_16x16x32_bf16 v[0:3], v[210:213], v[194:197], v[0:3]
	v_mfma_f32_16x16x32_bf16 v[48:51], v[206:209], v[174:177], v[48:51]
	v_mfma_f32_16x16x32_bf16 v[40:43], v[214:217], v[174:177], v[40:43]
	v_mfma_f32_16x16x32_bf16 v[32:35], v[206:209], v[182:185], v[32:35]
	v_mfma_f32_16x16x32_bf16 v[24:27], v[214:217], v[182:185], v[24:27]
	v_mfma_f32_16x16x32_bf16 v[16:19], v[206:209], v[190:193], v[16:19]
	v_mfma_f32_16x16x32_bf16 v[8:11], v[214:217], v[190:193], v[8:11]
	v_mfma_f32_16x16x32_bf16 v[4:7], v[206:209], v[198:201], v[4:7]
	v_mfma_f32_16x16x32_bf16 v[0:3], v[214:217], v[198:201], v[0:3]
	s_add_u32 s50, s50, 0x100
	s_addc_u32 s51, s51, 0
	s_add_u32 s41, s41, 0x100
	s_addc_u32 s43, s43, 0
	s_cmp_ge_i32 s77, s76
	s_mov_b32 s45, s77
	s_barrier
	s_cbranch_scc0 .LBB0_1146
	v_lshl_add_u32 v150, s8, 8, v133
	v_lshl_or_b32 v154, s44, 8, v162
	s_cmp_lg_u32 s75, 0
	v_ashrrev_i32_e32 v155, 31, v154
	v_or_b32_e32 v160, 16, v150
	v_or_b32_e32 v158, 32, v150
	v_or_b32_e32 v156, 48, v150
	s_cbranch_scc0 .LBB0_1149
	s_add_i32 s8, s75, -1
	s_lshl_b64 s[44:45], s[8:9], 21
	s_add_u32 s44, s92, s44
	s_addc_u32 s45, s93, s45
	v_lshl_add_u64 v[152:153], v[154:155], 2, s[44:45]
	v_ashrrev_i32_e32 v151, 31, v150
	v_ashrrev_i32_e32 v161, 31, v160
	v_lshl_add_u64 v[152:153], v[152:153], 0, s[22:23]
	v_lshlrev_b64 v[166:167], 12, v[150:151]
	v_lshlrev_b64 v[168:169], 12, v[160:161]
	v_lshl_add_u64 v[166:167], v[152:153], 0, v[166:167]
	v_lshl_add_u64 v[168:169], v[152:153], 0, v[168:169]
	v_ashrrev_i32_e32 v159, 31, v158
	global_store_dwordx4 v[166:167], v[124:127], off
	global_store_dwordx4 v[166:167], v[120:123], off offset:16
	global_store_dwordx4 v[166:167], v[112:115], off offset:512
	global_store_dwordx4 v[166:167], v[104:107], off offset:528
	global_store_dwordx4 v[168:169], v[116:119], off
	global_store_dwordx4 v[168:169], v[108:111], off offset:16
	global_store_dwordx4 v[168:169], v[96:99], off offset:512
	global_store_dwordx4 v[168:169], v[88:91], off offset:528
	v_lshlrev_b64 v[168:169], 12, v[158:159]
	v_lshl_add_u64 v[168:169], v[152:153], 0, v[168:169]
	v_ashrrev_i32_e32 v157, 31, v156
	global_store_dwordx4 v[168:169], v[100:103], off
	global_store_dwordx4 v[168:169], v[92:95], off offset:16
	global_store_dwordx4 v[168:169], v[80:83], off offset:512
	global_store_dwordx4 v[168:169], v[72:75], off offset:528
	v_lshlrev_b64 v[168:169], 12, v[156:157]
	v_lshl_add_u64 v[152:153], v[152:153], 0, v[168:169]
	v_add_co_u32_e32 v168, vcc, s68, v166
	global_store_dwordx4 v[152:153], v[84:87], off
	global_store_dwordx4 v[152:153], v[76:79], off offset:16
	global_store_dwordx4 v[152:153], v[68:71], off offset:512
	global_store_dwordx4 v[152:153], v[64:67], off offset:528
	v_addc_co_u32_e32 v169, vcc, 0, v167, vcc
	v_lshl_add_u64 v[152:153], v[166:167], 0, s[24:25]
	global_store_dwordx4 v[168:169], v[60:63], off
	global_store_dwordx4 v[152:153], v[56:59], off offset:16
	global_store_dwordx4 v[152:153], v[48:51], off offset:512
	global_store_dwordx4 v[152:153], v[40:43], off offset:528
	v_add_co_u32_e32 v168, vcc, s69, v166
	v_lshl_add_u64 v[152:153], v[166:167], 0, s[26:27]
	s_nop 0
	v_addc_co_u32_e32 v169, vcc, 0, v167, vcc
	global_store_dwordx4 v[168:169], v[52:55], off
	global_store_dwordx4 v[152:153], v[44:47], off offset:16
	global_store_dwordx4 v[152:153], v[32:35], off offset:512
	global_store_dwordx4 v[152:153], v[24:27], off offset:528
	v_add_co_u32_e32 v168, vcc, s70, v166
	v_lshl_add_u64 v[152:153], v[166:167], 0, s[28:29]
	s_nop 0
	v_addc_co_u32_e32 v169, vcc, 0, v167, vcc
	global_store_dwordx4 v[168:169], v[36:39], off
	global_store_dwordx4 v[152:153], v[28:31], off offset:16
	global_store_dwordx4 v[152:153], v[16:19], off offset:512
	global_store_dwordx4 v[152:153], v[8:11], off offset:528
	v_lshl_add_u64 v[152:153], v[166:167], 0, s[36:37]
	v_add_co_u32_e32 v166, vcc, 0xb0000, v166
	s_nop 1
	v_addc_co_u32_e32 v167, vcc, 0, v167, vcc
	global_store_dwordx4 v[166:167], v[20:23], off
	global_store_dwordx4 v[152:153], v[12:15], off offset:16
	global_store_dwordx4 v[152:153], v[4:7], off offset:512
	global_store_dwordx4 v[152:153], v[0:3], off offset:528
	s_cbranch_execnz .LBB0_1131
	s_branch .LBB0_1130
